# v81 + m0-hazard s_nop pads in GEMM K-loop load segments replaced by moved ds_reads (56 fewer instructions)
# baseline (speedup 1.0000x reference)
.LBB0_173:
	ds_read_b128 v[144:147], v155
	ds_read_b128 v[148:151], v155 offset:1024
	ds_read_b128 v[158:161], v155 offset:2048
	ds_read_b128 v[162:165], v155 offset:3072
	ds_read_b128 v[166:169], v156
	ds_read_b128 v[170:173], v156 offset:1024
	ds_read_b128 v[174:177], v156 offset:2048
	ds_read_b128 v[178:181], v156 offset:3072
	s_add_u32 s68, s66, 0xfff80080
	s_addc_u32 s69, s67, -1
	s_cmp_eq_u32 s77, 28
	s_cselect_b32 s71, s55, s69
	s_cselect_b32 s70, s59, s68
	s_cselect_b32 s69, s57, s76
	s_cselect_b32 s68, s65, s73
	s_add_i32 m0, s25, 0xc000
	ds_read_b128 v[182:185], v157
	ds_read_b128 v[186:189], v157 offset:1024
	ds_read_b128 v[190:193], v157 offset:2048
	ds_read_b128 v[194:197], v157 offset:3072
	ds_read_b128 v[198:201], v157 offset:4096
	ds_read_b128 v[202:205], v157 offset:5120
	ds_read_b128 v[206:209], v157 offset:6144
	global_load_lds_dwordx4 v136, s[66:67]
	s_add_i32 m0, s25, 0xe000
	ds_read_b128 v[210:213], v157 offset:7168
	global_load_lds_dwordx4 v138, s[66:67]
	s_waitcnt vmcnt(8) lgkmcnt(0)
	s_setprio 1
	s_barrier
	v_mfma_i32_16x16x64_i8 v[124:127], v[144:147], v[182:185], v[124:127]
	v_mfma_i32_16x16x64_i8 v[116:119], v[158:161], v[182:185], v[116:119]
	v_mfma_i32_16x16x64_i8 v[108:111], v[144:147], v[190:193], v[108:111]
	v_mfma_i32_16x16x64_i8 v[100:103], v[158:161], v[190:193], v[100:103]
	v_mfma_i32_16x16x64_i8 v[92:95], v[144:147], v[198:201], v[92:95]
	v_mfma_i32_16x16x64_i8 v[84:87], v[158:161], v[198:201], v[84:87]
	v_mfma_i32_16x16x64_i8 v[76:79], v[144:147], v[206:209], v[76:79]
	v_mfma_i32_16x16x64_i8 v[68:71], v[158:161], v[206:209], v[68:71]
	v_mfma_i32_16x16x64_i8 v[124:127], v[148:151], v[186:189], v[124:127]
	v_mfma_i32_16x16x64_i8 v[116:119], v[162:165], v[186:189], v[116:119]
	v_mfma_i32_16x16x64_i8 v[108:111], v[148:151], v[194:197], v[108:111]
	v_mfma_i32_16x16x64_i8 v[100:103], v[162:165], v[194:197], v[100:103]
	v_mfma_i32_16x16x64_i8 v[92:95], v[148:151], v[202:205], v[92:95]
	v_mfma_i32_16x16x64_i8 v[84:87], v[162:165], v[202:205], v[84:87]
	v_mfma_i32_16x16x64_i8 v[76:79], v[148:151], v[210:213], v[76:79]
	v_mfma_i32_16x16x64_i8 v[68:71], v[162:165], v[210:213], v[68:71]
	v_mfma_i32_16x16x64_i8 v[120:123], v[166:169], v[182:185], v[120:123]
	v_mfma_i32_16x16x64_i8 v[112:115], v[174:177], v[182:185], v[112:115]
	v_mfma_i32_16x16x64_i8 v[104:107], v[166:169], v[190:193], v[104:107]
	v_mfma_i32_16x16x64_i8 v[96:99], v[174:177], v[190:193], v[96:99]
	v_mfma_i32_16x16x64_i8 v[88:91], v[166:169], v[198:201], v[88:91]
	v_mfma_i32_16x16x64_i8 v[80:83], v[174:177], v[198:201], v[80:83]
	v_mfma_i32_16x16x64_i8 v[72:75], v[166:169], v[206:209], v[72:75]
	v_mfma_i32_16x16x64_i8 v[64:67], v[174:177], v[206:209], v[64:67]
	v_mfma_i32_16x16x64_i8 v[120:123], v[170:173], v[186:189], v[120:123]
	v_mfma_i32_16x16x64_i8 v[112:115], v[178:181], v[186:189], v[112:115]
	v_mfma_i32_16x16x64_i8 v[104:107], v[170:173], v[194:197], v[104:107]
	v_mfma_i32_16x16x64_i8 v[96:99], v[178:181], v[194:197], v[96:99]
	v_mfma_i32_16x16x64_i8 v[88:91], v[170:173], v[202:205], v[88:91]
	v_mfma_i32_16x16x64_i8 v[80:83], v[178:181], v[202:205], v[80:83]
	v_mfma_i32_16x16x64_i8 v[72:75], v[170:173], v[210:213], v[72:75]
	v_mfma_i32_16x16x64_i8 v[64:67], v[178:181], v[210:213], v[64:67]
	s_barrier
	s_setprio 0
	s_add_i32 s78, s35, s13
	s_mov_b32 m0, s78
	ds_read_b128 v[182:185], v157 offset:16384
	ds_read_b128 v[186:189], v157 offset:17408
	ds_read_b128 v[190:193], v157 offset:18432
	ds_read_b128 v[194:197], v157 offset:19456
	ds_read_b128 v[198:201], v157 offset:20480
	global_load_lds_dwordx4 v132, s[68:69]
	s_add_i32 m0, s78, 0x2000
	s_add_u32 s78, s68, 0x80000
	s_mov_b64 s[98:99], s[68:69]
	s_addc_u32 s79, s69, 0
	s_add_i32 s81, s52, s13
	global_load_lds_dwordx4 v128, s[98:99]
	s_mov_b32 m0, s81
	s_mov_b64 s[100:101], s[70:71]
	global_load_lds_dwordx4 v132, s[78:79]
	s_add_i32 m0, s81, 0x2000
	ds_read_b128 v[202:205], v157 offset:21504
	global_load_lds_dwordx4 v128, s[78:79]
	s_mov_b64 s[100:101], s[70:71]
	s_mov_b32 m0, s25
	ds_read_b128 v[206:209], v157 offset:22528
	global_load_lds_dwordx4 v134, s[100:101]
	s_mov_b32 m0, s26
	ds_read_b128 v[210:213], v157 offset:23552
	global_load_lds_dwordx4 v130, s[100:101]
	s_waitcnt vmcnt(8) lgkmcnt(0)
	s_setprio 1
	s_barrier
	v_mfma_i32_16x16x64_i8 v[60:63], v[144:147], v[182:185], v[60:63]
	v_mfma_i32_16x16x64_i8 v[52:55], v[158:161], v[182:185], v[52:55]
	v_mfma_i32_16x16x64_i8 v[44:47], v[144:147], v[190:193], v[44:47]
	v_mfma_i32_16x16x64_i8 v[36:39], v[158:161], v[190:193], v[36:39]
	v_mfma_i32_16x16x64_i8 v[28:31], v[144:147], v[198:201], v[28:31]
	v_mfma_i32_16x16x64_i8 v[20:23], v[158:161], v[198:201], v[20:23]
	v_mfma_i32_16x16x64_i8 v[12:15], v[144:147], v[206:209], v[12:15]
	v_mfma_i32_16x16x64_i8 v[4:7], v[158:161], v[206:209], v[4:7]
	v_mfma_i32_16x16x64_i8 v[60:63], v[148:151], v[186:189], v[60:63]
	v_mfma_i32_16x16x64_i8 v[52:55], v[162:165], v[186:189], v[52:55]
	v_mfma_i32_16x16x64_i8 v[44:47], v[148:151], v[194:197], v[44:47]
	v_mfma_i32_16x16x64_i8 v[36:39], v[162:165], v[194:197], v[36:39]
	v_mfma_i32_16x16x64_i8 v[28:31], v[148:151], v[202:205], v[28:31]
	v_mfma_i32_16x16x64_i8 v[20:23], v[162:165], v[202:205], v[20:23]
	v_mfma_i32_16x16x64_i8 v[12:15], v[148:151], v[210:213], v[12:15]
	v_mfma_i32_16x16x64_i8 v[4:7], v[162:165], v[210:213], v[4:7]
	v_mfma_i32_16x16x64_i8 v[56:59], v[166:169], v[182:185], v[56:59]
	v_mfma_i32_16x16x64_i8 v[48:51], v[174:177], v[182:185], v[48:51]
	v_mfma_i32_16x16x64_i8 v[40:43], v[166:169], v[190:193], v[40:43]
	v_mfma_i32_16x16x64_i8 v[32:35], v[174:177], v[190:193], v[32:35]
	v_mfma_i32_16x16x64_i8 v[24:27], v[166:169], v[198:201], v[24:27]
	v_mfma_i32_16x16x64_i8 v[16:19], v[174:177], v[198:201], v[16:19]
	v_mfma_i32_16x16x64_i8 v[8:11], v[166:169], v[206:209], v[8:11]
	v_mfma_i32_16x16x64_i8 v[0:3], v[174:177], v[206:209], v[0:3]
	v_mfma_i32_16x16x64_i8 v[56:59], v[170:173], v[186:189], v[56:59]
	v_mfma_i32_16x16x64_i8 v[48:51], v[178:181], v[186:189], v[48:51]
	v_mfma_i32_16x16x64_i8 v[40:43], v[170:173], v[194:197], v[40:43]
	v_mfma_i32_16x16x64_i8 v[32:35], v[178:181], v[194:197], v[32:35]
	v_mfma_i32_16x16x64_i8 v[24:27], v[170:173], v[202:205], v[24:27]
	v_mfma_i32_16x16x64_i8 v[16:19], v[178:181], v[202:205], v[16:19]
	v_mfma_i32_16x16x64_i8 v[8:11], v[170:173], v[210:213], v[8:11]
	v_mfma_i32_16x16x64_i8 v[0:3], v[178:181], v[210:213], v[0:3]
	s_barrier
	s_setprio 0
	s_add_i32 s78, 0, 0x18000
	s_add_i32 s79, 0, 0x1c000
	ds_read_b128 v[144:147], v155 offset:32768
	ds_read_b128 v[148:151], v155 offset:33792
	ds_read_b128 v[158:161], v155 offset:34816
	ds_read_b128 v[162:165], v155 offset:35840
	ds_read_b128 v[166:169], v156 offset:32768
	ds_read_b128 v[170:173], v156 offset:33792
	ds_read_b128 v[174:177], v156 offset:34816
	ds_read_b128 v[178:181], v156 offset:35840
	s_add_u32 s70, s70, 0x80000
	s_addc_u32 s71, s71, 0
	s_mov_b32 m0, s27
	ds_read_b128 v[182:185], v157 offset:32768
	ds_read_b128 v[186:189], v157 offset:33792
	ds_read_b128 v[190:193], v157 offset:34816
	ds_read_b128 v[194:197], v157 offset:35840
	ds_read_b128 v[198:201], v157 offset:36864
	ds_read_b128 v[202:205], v157 offset:37888
	ds_read_b128 v[206:209], v157 offset:38912
	global_load_lds_dwordx4 v134, s[70:71]
	s_mov_b32 m0, s28
	ds_read_b128 v[210:213], v157 offset:39936
	global_load_lds_dwordx4 v130, s[70:71]
	s_waitcnt vmcnt(8) lgkmcnt(0)
	s_setprio 1
	s_barrier
	v_mfma_i32_16x16x64_i8 v[124:127], v[144:147], v[182:185], v[124:127]
	v_mfma_i32_16x16x64_i8 v[116:119], v[158:161], v[182:185], v[116:119]
	v_mfma_i32_16x16x64_i8 v[108:111], v[144:147], v[190:193], v[108:111]
	v_mfma_i32_16x16x64_i8 v[100:103], v[158:161], v[190:193], v[100:103]
	v_mfma_i32_16x16x64_i8 v[92:95], v[144:147], v[198:201], v[92:95]
	v_mfma_i32_16x16x64_i8 v[84:87], v[158:161], v[198:201], v[84:87]
	v_mfma_i32_16x16x64_i8 v[76:79], v[144:147], v[206:209], v[76:79]
	v_mfma_i32_16x16x64_i8 v[68:71], v[158:161], v[206:209], v[68:71]
	v_mfma_i32_16x16x64_i8 v[124:127], v[148:151], v[186:189], v[124:127]
	v_mfma_i32_16x16x64_i8 v[116:119], v[162:165], v[186:189], v[116:119]
	v_mfma_i32_16x16x64_i8 v[108:111], v[148:151], v[194:197], v[108:111]
	v_mfma_i32_16x16x64_i8 v[100:103], v[162:165], v[194:197], v[100:103]
	v_mfma_i32_16x16x64_i8 v[92:95], v[148:151], v[202:205], v[92:95]
	v_mfma_i32_16x16x64_i8 v[84:87], v[162:165], v[202:205], v[84:87]
	v_mfma_i32_16x16x64_i8 v[76:79], v[148:151], v[210:213], v[76:79]
	v_mfma_i32_16x16x64_i8 v[68:71], v[162:165], v[210:213], v[68:71]
	v_mfma_i32_16x16x64_i8 v[120:123], v[166:169], v[182:185], v[120:123]
	v_mfma_i32_16x16x64_i8 v[112:115], v[174:177], v[182:185], v[112:115]
	v_mfma_i32_16x16x64_i8 v[104:107], v[166:169], v[190:193], v[104:107]
	v_mfma_i32_16x16x64_i8 v[96:99], v[174:177], v[190:193], v[96:99]
	v_mfma_i32_16x16x64_i8 v[88:91], v[166:169], v[198:201], v[88:91]
	v_mfma_i32_16x16x64_i8 v[80:83], v[174:177], v[198:201], v[80:83]
	v_mfma_i32_16x16x64_i8 v[72:75], v[166:169], v[206:209], v[72:75]
	v_mfma_i32_16x16x64_i8 v[64:67], v[174:177], v[206:209], v[64:67]
	v_mfma_i32_16x16x64_i8 v[120:123], v[170:173], v[186:189], v[120:123]
	v_mfma_i32_16x16x64_i8 v[112:115], v[178:181], v[186:189], v[112:115]
	v_mfma_i32_16x16x64_i8 v[104:107], v[170:173], v[194:197], v[104:107]
	v_mfma_i32_16x16x64_i8 v[96:99], v[178:181], v[194:197], v[96:99]
	v_mfma_i32_16x16x64_i8 v[88:91], v[170:173], v[202:205], v[88:91]
	v_mfma_i32_16x16x64_i8 v[80:83], v[178:181], v[202:205], v[80:83]
	v_mfma_i32_16x16x64_i8 v[72:75], v[170:173], v[210:213], v[72:75]
	v_mfma_i32_16x16x64_i8 v[64:67], v[178:181], v[210:213], v[64:67]
	s_barrier
	s_setprio 0
	s_add_i32 s70, s78, s13
	s_add_i32 m0, s70, -128
	ds_read_b128 v[182:185], v157 offset:49152
	ds_read_b128 v[186:189], v157 offset:50176
	ds_read_b128 v[190:193], v157 offset:51200
	ds_read_b128 v[194:197], v157 offset:52224
	global_load_lds_dwordx4 v132, s[68:69] offset:128
	s_add_i32 m0, s70, 8064
	s_add_u32 s68, s68, 0x80080
	s_addc_u32 s69, s69, 0
	s_add_i32 s70, s79, s13
	global_load_lds_dwordx4 v128, s[98:99] offset:128
	s_mov_b32 m0, s70
	ds_read_b128 v[198:201], v157 offset:53248
	global_load_lds_dwordx4 v132, s[68:69]
	s_add_i32 m0, s70, 0x2000
	ds_read_b128 v[202:205], v157 offset:54272
	global_load_lds_dwordx4 v128, s[68:69]
	s_add_i32 m0, s31, -128
	ds_read_b128 v[206:209], v157 offset:55296
	global_load_lds_dwordx4 v134, s[100:101] offset:128
	s_add_i32 m0, s33, -128
	ds_read_b128 v[210:213], v157 offset:56320
	global_load_lds_dwordx4 v130, s[100:101] offset:128
	s_waitcnt vmcnt(8) lgkmcnt(0)
	s_setprio 1
	s_barrier
	v_mfma_i32_16x16x64_i8 v[60:63], v[144:147], v[182:185], v[60:63]
	v_mfma_i32_16x16x64_i8 v[52:55], v[158:161], v[182:185], v[52:55]
	v_mfma_i32_16x16x64_i8 v[44:47], v[144:147], v[190:193], v[44:47]
	v_mfma_i32_16x16x64_i8 v[36:39], v[158:161], v[190:193], v[36:39]
	v_mfma_i32_16x16x64_i8 v[28:31], v[144:147], v[198:201], v[28:31]
	v_mfma_i32_16x16x64_i8 v[20:23], v[158:161], v[198:201], v[20:23]
	v_mfma_i32_16x16x64_i8 v[12:15], v[144:147], v[206:209], v[12:15]
	v_mfma_i32_16x16x64_i8 v[4:7], v[158:161], v[206:209], v[4:7]
	v_mfma_i32_16x16x64_i8 v[60:63], v[148:151], v[186:189], v[60:63]
	v_mfma_i32_16x16x64_i8 v[52:55], v[162:165], v[186:189], v[52:55]
	v_mfma_i32_16x16x64_i8 v[44:47], v[148:151], v[194:197], v[44:47]
	v_mfma_i32_16x16x64_i8 v[36:39], v[162:165], v[194:197], v[36:39]
	v_mfma_i32_16x16x64_i8 v[28:31], v[148:151], v[202:205], v[28:31]
	v_mfma_i32_16x16x64_i8 v[20:23], v[162:165], v[202:205], v[20:23]
	v_mfma_i32_16x16x64_i8 v[12:15], v[148:151], v[210:213], v[12:15]
	v_mfma_i32_16x16x64_i8 v[4:7], v[162:165], v[210:213], v[4:7]
	v_mfma_i32_16x16x64_i8 v[56:59], v[166:169], v[182:185], v[56:59]
	v_mfma_i32_16x16x64_i8 v[48:51], v[174:177], v[182:185], v[48:51]
	v_mfma_i32_16x16x64_i8 v[40:43], v[166:169], v[190:193], v[40:43]
	v_mfma_i32_16x16x64_i8 v[32:35], v[174:177], v[190:193], v[32:35]
	v_mfma_i32_16x16x64_i8 v[24:27], v[166:169], v[198:201], v[24:27]
	v_mfma_i32_16x16x64_i8 v[16:19], v[174:177], v[198:201], v[16:19]
	v_mfma_i32_16x16x64_i8 v[8:11], v[166:169], v[206:209], v[8:11]
	v_mfma_i32_16x16x64_i8 v[0:3], v[174:177], v[206:209], v[0:3]
	v_mfma_i32_16x16x64_i8 v[56:59], v[170:173], v[186:189], v[56:59]
	v_mfma_i32_16x16x64_i8 v[48:51], v[178:181], v[186:189], v[48:51]
	v_mfma_i32_16x16x64_i8 v[40:43], v[170:173], v[194:197], v[40:43]
	v_mfma_i32_16x16x64_i8 v[32:35], v[178:181], v[194:197], v[32:35]
	v_mfma_i32_16x16x64_i8 v[24:27], v[170:173], v[202:205], v[24:27]
	v_mfma_i32_16x16x64_i8 v[16:19], v[178:181], v[202:205], v[16:19]
	v_mfma_i32_16x16x64_i8 v[8:11], v[170:173], v[210:213], v[8:11]
	v_mfma_i32_16x16x64_i8 v[0:3], v[178:181], v[210:213], v[0:3]
	s_barrier
	s_setprio 0
	s_add_i32 s77, s77, 2
	s_add_u32 s66, s66, 0x100
	s_addc_u32 s67, s67, 0
	s_add_u32 s73, s73, 0x100
	s_addc_u32 s76, s76, 0
	s_cmp_gt_u32 s77, 29
	s_cbranch_scc0 .LBB0_173
	s_and_b64 vcc, exec, s[20:21]
	s_cbranch_vccz .LBB0_176
	s_barrier

.LBB0_258:
	ds_read_b128 v[152:155], v149
	ds_read_b128 v[156:159], v149 offset:1024
	ds_read_b128 v[160:163], v149 offset:2048
	ds_read_b128 v[164:167], v149 offset:3072
	ds_read_b128 v[168:171], v150
	ds_read_b128 v[172:175], v150 offset:1024
	ds_read_b128 v[176:179], v150 offset:2048
	ds_read_b128 v[180:183], v150 offset:3072
	s_add_u32 s36, s22, 0x100
	s_addc_u32 s37, s23, 0
	s_cmpk_eq_i32 s62, 0xa8
	s_cselect_b32 s57, s5, s37
	s_cselect_b32 s56, s4, s36
	s_cselect_b32 s41, s21, s61
	s_cselect_b32 s40, s20, s60
	s_add_i32 m0, s25, 0xc000
	ds_read_b128 v[184:187], v151
	ds_read_b128 v[188:191], v151 offset:1024
	ds_read_b128 v[192:195], v151 offset:2048
	ds_read_b128 v[196:199], v151 offset:3072
	ds_read_b128 v[200:203], v151 offset:4096
	ds_read_b128 v[204:207], v151 offset:5120
	ds_read_b128 v[208:211], v151 offset:6144
	global_load_lds_dwordx4 v136, s[22:23]
	s_add_i32 m0, s25, 0xe000
	ds_read_b128 v[212:215], v151 offset:7168
	global_load_lds_dwordx4 v138, s[22:23]
	s_waitcnt vmcnt(8) lgkmcnt(0)
	s_setprio 1
	s_barrier
	v_mfma_f32_16x16x32_bf16 v[124:127], v[152:155], v[184:187], v[124:127]
	v_mfma_f32_16x16x32_bf16 v[120:123], v[160:163], v[184:187], v[120:123]
	v_mfma_f32_16x16x32_bf16 v[116:119], v[152:155], v[192:195], v[116:119]
	v_mfma_f32_16x16x32_bf16 v[108:111], v[160:163], v[192:195], v[108:111]
	v_mfma_f32_16x16x32_bf16 v[100:103], v[152:155], v[200:203], v[100:103]
	v_mfma_f32_16x16x32_bf16 v[92:95], v[160:163], v[200:203], v[92:95]
	v_mfma_f32_16x16x32_bf16 v[84:87], v[152:155], v[208:211], v[84:87]
	v_mfma_f32_16x16x32_bf16 v[76:79], v[160:163], v[208:211], v[76:79]
	v_mfma_f32_16x16x32_bf16 v[124:127], v[156:159], v[188:191], v[124:127]
	v_mfma_f32_16x16x32_bf16 v[120:123], v[164:167], v[188:191], v[120:123]
	v_mfma_f32_16x16x32_bf16 v[116:119], v[156:159], v[196:199], v[116:119]
	v_mfma_f32_16x16x32_bf16 v[108:111], v[164:167], v[196:199], v[108:111]
	v_mfma_f32_16x16x32_bf16 v[100:103], v[156:159], v[204:207], v[100:103]
	v_mfma_f32_16x16x32_bf16 v[92:95], v[164:167], v[204:207], v[92:95]
	v_mfma_f32_16x16x32_bf16 v[84:87], v[156:159], v[212:215], v[84:87]
	v_mfma_f32_16x16x32_bf16 v[76:79], v[164:167], v[212:215], v[76:79]
	v_mfma_f32_16x16x32_bf16 v[112:115], v[168:171], v[184:187], v[112:115]
	v_mfma_f32_16x16x32_bf16 v[104:107], v[176:179], v[184:187], v[104:107]
	v_mfma_f32_16x16x32_bf16 v[96:99], v[168:171], v[192:195], v[96:99]
	v_mfma_f32_16x16x32_bf16 v[88:91], v[176:179], v[192:195], v[88:91]
	v_mfma_f32_16x16x32_bf16 v[80:83], v[168:171], v[200:203], v[80:83]
	v_mfma_f32_16x16x32_bf16 v[72:75], v[176:179], v[200:203], v[72:75]
	v_mfma_f32_16x16x32_bf16 v[68:71], v[168:171], v[208:211], v[68:71]
	v_mfma_f32_16x16x32_bf16 v[64:67], v[176:179], v[208:211], v[64:67]
	v_mfma_f32_16x16x32_bf16 v[112:115], v[172:175], v[188:191], v[112:115]
	v_mfma_f32_16x16x32_bf16 v[104:107], v[180:183], v[188:191], v[104:107]
	v_mfma_f32_16x16x32_bf16 v[96:99], v[172:175], v[196:199], v[96:99]
	v_mfma_f32_16x16x32_bf16 v[88:91], v[180:183], v[196:199], v[88:91]
	v_mfma_f32_16x16x32_bf16 v[80:83], v[172:175], v[204:207], v[80:83]
	v_mfma_f32_16x16x32_bf16 v[72:75], v[180:183], v[204:207], v[72:75]
	v_mfma_f32_16x16x32_bf16 v[68:71], v[172:175], v[212:215], v[68:71]
	v_mfma_f32_16x16x32_bf16 v[64:67], v[180:183], v[212:215], v[64:67]
	s_barrier
	s_setprio 0
	s_add_i32 s22, s35, s3
	s_mov_b32 m0, s22
	ds_read_b128 v[184:187], v151 offset:16384
	ds_read_b128 v[188:191], v151 offset:17408
	ds_read_b128 v[192:195], v151 offset:18432
	ds_read_b128 v[196:199], v151 offset:19456
	global_load_lds_dwordx4 v132, s[40:41]
	s_add_i32 m0, s22, 0x2000
	s_add_u32 s22, s40, 0x2b0000
	s_mov_b64 s[98:99], s[40:41]
	s_addc_u32 s23, s41, 0
	s_add_i32 s63, s52, s3
	global_load_lds_dwordx4 v128, s[98:99]
	s_mov_b32 m0, s63
	ds_read_b128 v[200:203], v151 offset:20480
	global_load_lds_dwordx4 v132, s[22:23]
	s_add_i32 m0, s63, 0x2000
	ds_read_b128 v[204:207], v151 offset:21504
	global_load_lds_dwordx4 v128, s[22:23]
	s_mov_b32 m0, s25
	ds_read_b128 v[208:211], v151 offset:22528
	global_load_lds_dwordx4 v134, s[56:57]
	s_mov_b32 m0, s26
	ds_read_b128 v[212:215], v151 offset:23552
	global_load_lds_dwordx4 v130, s[56:57]
	s_waitcnt vmcnt(8) lgkmcnt(0)
	s_setprio 1
	s_barrier
	v_mfma_f32_16x16x32_bf16 v[60:63], v[152:155], v[184:187], v[60:63]
	v_mfma_f32_16x16x32_bf16 v[56:59], v[160:163], v[184:187], v[56:59]
	v_mfma_f32_16x16x32_bf16 v[52:55], v[152:155], v[192:195], v[52:55]
	v_mfma_f32_16x16x32_bf16 v[44:47], v[160:163], v[192:195], v[44:47]
	v_mfma_f32_16x16x32_bf16 v[36:39], v[152:155], v[200:203], v[36:39]
	v_mfma_f32_16x16x32_bf16 v[28:31], v[160:163], v[200:203], v[28:31]
	v_mfma_f32_16x16x32_bf16 v[20:23], v[152:155], v[208:211], v[20:23]
	v_mfma_f32_16x16x32_bf16 v[12:15], v[160:163], v[208:211], v[12:15]
	v_mfma_f32_16x16x32_bf16 v[60:63], v[156:159], v[188:191], v[60:63]
	v_mfma_f32_16x16x32_bf16 v[56:59], v[164:167], v[188:191], v[56:59]
	v_mfma_f32_16x16x32_bf16 v[52:55], v[156:159], v[196:199], v[52:55]
	v_mfma_f32_16x16x32_bf16 v[44:47], v[164:167], v[196:199], v[44:47]
	v_mfma_f32_16x16x32_bf16 v[36:39], v[156:159], v[204:207], v[36:39]
	v_mfma_f32_16x16x32_bf16 v[28:31], v[164:167], v[204:207], v[28:31]
	v_mfma_f32_16x16x32_bf16 v[20:23], v[156:159], v[212:215], v[20:23]
	v_mfma_f32_16x16x32_bf16 v[12:15], v[164:167], v[212:215], v[12:15]
	v_mfma_f32_16x16x32_bf16 v[48:51], v[168:171], v[184:187], v[48:51]
	v_mfma_f32_16x16x32_bf16 v[40:43], v[176:179], v[184:187], v[40:43]
	v_mfma_f32_16x16x32_bf16 v[32:35], v[168:171], v[192:195], v[32:35]
	v_mfma_f32_16x16x32_bf16 v[24:27], v[176:179], v[192:195], v[24:27]
	v_mfma_f32_16x16x32_bf16 v[16:19], v[168:171], v[200:203], v[16:19]
	v_mfma_f32_16x16x32_bf16 v[8:11], v[176:179], v[200:203], v[8:11]
	v_mfma_f32_16x16x32_bf16 v[4:7], v[168:171], v[208:211], v[4:7]
	v_mfma_f32_16x16x32_bf16 v[0:3], v[176:179], v[208:211], v[0:3]
	v_mfma_f32_16x16x32_bf16 v[48:51], v[172:175], v[188:191], v[48:51]
	v_mfma_f32_16x16x32_bf16 v[40:43], v[180:183], v[188:191], v[40:43]
	v_mfma_f32_16x16x32_bf16 v[32:35], v[172:175], v[196:199], v[32:35]
	v_mfma_f32_16x16x32_bf16 v[24:27], v[180:183], v[196:199], v[24:27]
	v_mfma_f32_16x16x32_bf16 v[16:19], v[172:175], v[204:207], v[16:19]
	v_mfma_f32_16x16x32_bf16 v[8:11], v[180:183], v[204:207], v[8:11]
	v_mfma_f32_16x16x32_bf16 v[4:7], v[172:175], v[212:215], v[4:7]
	v_mfma_f32_16x16x32_bf16 v[0:3], v[180:183], v[212:215], v[0:3]
	s_barrier
	s_setprio 0
	s_add_i32 s63, 0, 0x18000
	s_add_i32 s64, 0, 0x1c000
	ds_read_b128 v[152:155], v149 offset:32768
	ds_read_b128 v[156:159], v149 offset:33792
	ds_read_b128 v[160:163], v149 offset:34816
	ds_read_b128 v[164:167], v149 offset:35840
	ds_read_b128 v[168:171], v150 offset:32768
	ds_read_b128 v[172:175], v150 offset:33792
	ds_read_b128 v[176:179], v150 offset:34816
	ds_read_b128 v[180:183], v150 offset:35840
	s_add_u32 s22, s56, 0x2b0000
	s_addc_u32 s23, s57, 0
	s_mov_b32 m0, s27
	ds_read_b128 v[184:187], v151 offset:32768
	ds_read_b128 v[188:191], v151 offset:33792
	ds_read_b128 v[192:195], v151 offset:34816
	ds_read_b128 v[196:199], v151 offset:35840
	ds_read_b128 v[200:203], v151 offset:36864
	ds_read_b128 v[204:207], v151 offset:37888
	ds_read_b128 v[208:211], v151 offset:38912
	global_load_lds_dwordx4 v134, s[22:23]
	s_mov_b32 m0, s28
	ds_read_b128 v[212:215], v151 offset:39936
	global_load_lds_dwordx4 v130, s[22:23]
	s_waitcnt vmcnt(8) lgkmcnt(0)
	s_setprio 1
	s_barrier
	v_mfma_f32_16x16x32_bf16 v[124:127], v[152:155], v[184:187], v[124:127]
	v_mfma_f32_16x16x32_bf16 v[120:123], v[160:163], v[184:187], v[120:123]
	v_mfma_f32_16x16x32_bf16 v[116:119], v[152:155], v[192:195], v[116:119]
	v_mfma_f32_16x16x32_bf16 v[108:111], v[160:163], v[192:195], v[108:111]
	v_mfma_f32_16x16x32_bf16 v[100:103], v[152:155], v[200:203], v[100:103]
	v_mfma_f32_16x16x32_bf16 v[92:95], v[160:163], v[200:203], v[92:95]
	v_mfma_f32_16x16x32_bf16 v[84:87], v[152:155], v[208:211], v[84:87]
	v_mfma_f32_16x16x32_bf16 v[76:79], v[160:163], v[208:211], v[76:79]
	v_mfma_f32_16x16x32_bf16 v[124:127], v[156:159], v[188:191], v[124:127]
	v_mfma_f32_16x16x32_bf16 v[120:123], v[164:167], v[188:191], v[120:123]
	v_mfma_f32_16x16x32_bf16 v[116:119], v[156:159], v[196:199], v[116:119]
	v_mfma_f32_16x16x32_bf16 v[108:111], v[164:167], v[196:199], v[108:111]
	v_mfma_f32_16x16x32_bf16 v[100:103], v[156:159], v[204:207], v[100:103]
	v_mfma_f32_16x16x32_bf16 v[92:95], v[164:167], v[204:207], v[92:95]
	v_mfma_f32_16x16x32_bf16 v[84:87], v[156:159], v[212:215], v[84:87]
	v_mfma_f32_16x16x32_bf16 v[76:79], v[164:167], v[212:215], v[76:79]
	v_mfma_f32_16x16x32_bf16 v[112:115], v[168:171], v[184:187], v[112:115]
	v_mfma_f32_16x16x32_bf16 v[104:107], v[176:179], v[184:187], v[104:107]
	v_mfma_f32_16x16x32_bf16 v[96:99], v[168:171], v[192:195], v[96:99]
	v_mfma_f32_16x16x32_bf16 v[88:91], v[176:179], v[192:195], v[88:91]
	v_mfma_f32_16x16x32_bf16 v[80:83], v[168:171], v[200:203], v[80:83]
	v_mfma_f32_16x16x32_bf16 v[72:75], v[176:179], v[200:203], v[72:75]
	v_mfma_f32_16x16x32_bf16 v[68:71], v[168:171], v[208:211], v[68:71]
	v_mfma_f32_16x16x32_bf16 v[64:67], v[176:179], v[208:211], v[64:67]
	v_mfma_f32_16x16x32_bf16 v[112:115], v[172:175], v[188:191], v[112:115]
	v_mfma_f32_16x16x32_bf16 v[104:107], v[180:183], v[188:191], v[104:107]
	v_mfma_f32_16x16x32_bf16 v[96:99], v[172:175], v[196:199], v[96:99]
	v_mfma_f32_16x16x32_bf16 v[88:91], v[180:183], v[196:199], v[88:91]
	v_mfma_f32_16x16x32_bf16 v[80:83], v[172:175], v[204:207], v[80:83]
	v_mfma_f32_16x16x32_bf16 v[72:75], v[180:183], v[204:207], v[72:75]
	v_mfma_f32_16x16x32_bf16 v[68:71], v[172:175], v[212:215], v[68:71]
	v_mfma_f32_16x16x32_bf16 v[64:67], v[180:183], v[212:215], v[64:67]
	s_barrier
	s_setprio 0
	s_add_i32 s22, s63, s3
	s_add_i32 m0, s22, -128
	ds_read_b128 v[184:187], v151 offset:49152
	ds_read_b128 v[188:191], v151 offset:50176
	ds_read_b128 v[192:195], v151 offset:51200
	ds_read_b128 v[196:199], v151 offset:52224
	global_load_lds_dwordx4 v132, s[40:41] offset:128
	s_add_i32 m0, s22, 8064
	s_add_u32 s22, s40, 0x2b0080
	s_addc_u32 s23, s41, 0
	s_add_i32 s40, s64, s3
	global_load_lds_dwordx4 v128, s[98:99] offset:128
	s_mov_b32 m0, s40
	ds_read_b128 v[200:203], v151 offset:53248
	global_load_lds_dwordx4 v132, s[22:23]
	s_add_i32 m0, s40, 0x2000
	ds_read_b128 v[204:207], v151 offset:54272
	global_load_lds_dwordx4 v128, s[22:23]
	s_add_i32 m0, s31, -128
	ds_read_b128 v[208:211], v151 offset:55296
	global_load_lds_dwordx4 v134, s[56:57] offset:128
	s_add_i32 m0, s33, -128
	ds_read_b128 v[212:215], v151 offset:56320
	global_load_lds_dwordx4 v130, s[56:57] offset:128
	s_waitcnt vmcnt(8) lgkmcnt(0)
	s_setprio 1
	s_barrier
	v_mfma_f32_16x16x32_bf16 v[60:63], v[152:155], v[184:187], v[60:63]
	v_mfma_f32_16x16x32_bf16 v[56:59], v[160:163], v[184:187], v[56:59]
	v_mfma_f32_16x16x32_bf16 v[52:55], v[152:155], v[192:195], v[52:55]
	v_mfma_f32_16x16x32_bf16 v[44:47], v[160:163], v[192:195], v[44:47]
	v_mfma_f32_16x16x32_bf16 v[36:39], v[152:155], v[200:203], v[36:39]
	v_mfma_f32_16x16x32_bf16 v[28:31], v[160:163], v[200:203], v[28:31]
	v_mfma_f32_16x16x32_bf16 v[20:23], v[152:155], v[208:211], v[20:23]
	v_mfma_f32_16x16x32_bf16 v[12:15], v[160:163], v[208:211], v[12:15]
	v_mfma_f32_16x16x32_bf16 v[60:63], v[156:159], v[188:191], v[60:63]
	v_mfma_f32_16x16x32_bf16 v[56:59], v[164:167], v[188:191], v[56:59]
	v_mfma_f32_16x16x32_bf16 v[52:55], v[156:159], v[196:199], v[52:55]
	v_mfma_f32_16x16x32_bf16 v[44:47], v[164:167], v[196:199], v[44:47]
	v_mfma_f32_16x16x32_bf16 v[36:39], v[156:159], v[204:207], v[36:39]
	v_mfma_f32_16x16x32_bf16 v[28:31], v[164:167], v[204:207], v[28:31]
	v_mfma_f32_16x16x32_bf16 v[20:23], v[156:159], v[212:215], v[20:23]
	v_mfma_f32_16x16x32_bf16 v[12:15], v[164:167], v[212:215], v[12:15]
	v_mfma_f32_16x16x32_bf16 v[48:51], v[168:171], v[184:187], v[48:51]
	v_mfma_f32_16x16x32_bf16 v[40:43], v[176:179], v[184:187], v[40:43]
	v_mfma_f32_16x16x32_bf16 v[32:35], v[168:171], v[192:195], v[32:35]
	v_mfma_f32_16x16x32_bf16 v[24:27], v[176:179], v[192:195], v[24:27]
	v_mfma_f32_16x16x32_bf16 v[16:19], v[168:171], v[200:203], v[16:19]
	v_mfma_f32_16x16x32_bf16 v[8:11], v[176:179], v[200:203], v[8:11]
	v_mfma_f32_16x16x32_bf16 v[4:7], v[168:171], v[208:211], v[4:7]
	v_mfma_f32_16x16x32_bf16 v[0:3], v[176:179], v[208:211], v[0:3]
	v_mfma_f32_16x16x32_bf16 v[48:51], v[172:175], v[188:191], v[48:51]
	v_mfma_f32_16x16x32_bf16 v[40:43], v[180:183], v[188:191], v[40:43]
	v_mfma_f32_16x16x32_bf16 v[32:35], v[172:175], v[196:199], v[32:35]
	v_mfma_f32_16x16x32_bf16 v[24:27], v[180:183], v[196:199], v[24:27]
	v_mfma_f32_16x16x32_bf16 v[16:19], v[172:175], v[204:207], v[16:19]
	v_mfma_f32_16x16x32_bf16 v[8:11], v[180:183], v[204:207], v[8:11]
	v_mfma_f32_16x16x32_bf16 v[4:7], v[172:175], v[212:215], v[4:7]
	v_mfma_f32_16x16x32_bf16 v[0:3], v[180:183], v[212:215], v[0:3]
	s_barrier
	s_setprio 0
	s_add_i32 s62, s62, 2
	s_add_u32 s60, s60, 0x100
	s_addc_u32 s61, s61, 0
	s_cmpk_gt_u32 s62, 0xa9
	s_mov_b64 s[22:23], s[36:37]
	s_cbranch_scc0 .LBB0_258
	s_and_b64 vcc, exec, s[14:15]
	s_cbranch_vccz .LBB0_261
	s_barrier

.LBB0_394:
	ds_read_b128 v[156:159], v152
	ds_read_b128 v[160:163], v152 offset:1024
	ds_read_b128 v[164:167], v152 offset:2048
	ds_read_b128 v[168:171], v152 offset:3072
	ds_read_b128 v[172:175], v153
	ds_read_b128 v[176:179], v153 offset:1024
	ds_read_b128 v[180:183], v153 offset:2048
	ds_read_b128 v[184:187], v153 offset:3072
	s_add_u32 s40, s38, 0xfff00080
	s_addc_u32 s41, s39, -1
	s_cmp_eq_u32 s64, 60
	s_cselect_b32 s57, s21, s41
	s_cselect_b32 s56, s60, s40
	s_cselect_b32 s41, s15, s63
	s_cselect_b32 s40, s61, s62
	s_add_i32 m0, s29, 0xc000
	ds_read_b128 v[188:191], v154
	ds_read_b128 v[192:195], v154 offset:1024
	ds_read_b128 v[196:199], v154 offset:2048
	ds_read_b128 v[200:203], v154 offset:3072
	ds_read_b128 v[204:207], v154 offset:4096
	ds_read_b128 v[208:211], v154 offset:5120
	ds_read_b128 v[212:215], v154 offset:6144
	global_load_lds_dwordx4 v140, s[38:39]
	s_add_i32 m0, s29, 0xe000
	ds_read_b128 v[216:219], v154 offset:7168
	global_load_lds_dwordx4 v142, s[38:39]
	s_waitcnt vmcnt(8) lgkmcnt(0)
	s_setprio 1
	s_barrier
	v_mfma_f32_16x16x32_bf16 v[124:127], v[156:159], v[188:191], v[124:127]
	v_mfma_f32_16x16x32_bf16 v[120:123], v[164:167], v[188:191], v[120:123]
	v_mfma_f32_16x16x32_bf16 v[112:115], v[156:159], v[196:199], v[112:115]
	v_mfma_f32_16x16x32_bf16 v[104:107], v[164:167], v[196:199], v[104:107]
	v_mfma_f32_16x16x32_bf16 v[96:99], v[156:159], v[204:207], v[96:99]
	v_mfma_f32_16x16x32_bf16 v[88:91], v[164:167], v[204:207], v[88:91]
	v_mfma_f32_16x16x32_bf16 v[80:83], v[156:159], v[212:215], v[80:83]
	v_mfma_f32_16x16x32_bf16 v[72:75], v[164:167], v[212:215], v[72:75]
	v_mfma_f32_16x16x32_bf16 v[124:127], v[160:163], v[192:195], v[124:127]
	v_mfma_f32_16x16x32_bf16 v[120:123], v[168:171], v[192:195], v[120:123]
	v_mfma_f32_16x16x32_bf16 v[112:115], v[160:163], v[200:203], v[112:115]
	v_mfma_f32_16x16x32_bf16 v[104:107], v[168:171], v[200:203], v[104:107]
	v_mfma_f32_16x16x32_bf16 v[96:99], v[160:163], v[208:211], v[96:99]
	v_mfma_f32_16x16x32_bf16 v[88:91], v[168:171], v[208:211], v[88:91]
	v_mfma_f32_16x16x32_bf16 v[80:83], v[160:163], v[216:219], v[80:83]
	v_mfma_f32_16x16x32_bf16 v[72:75], v[168:171], v[216:219], v[72:75]
	v_mfma_f32_16x16x32_bf16 v[116:119], v[172:175], v[188:191], v[116:119]
	v_mfma_f32_16x16x32_bf16 v[108:111], v[180:183], v[188:191], v[108:111]
	v_mfma_f32_16x16x32_bf16 v[100:103], v[172:175], v[196:199], v[100:103]
	v_mfma_f32_16x16x32_bf16 v[92:95], v[180:183], v[196:199], v[92:95]
	v_mfma_f32_16x16x32_bf16 v[84:87], v[172:175], v[204:207], v[84:87]
	v_mfma_f32_16x16x32_bf16 v[76:79], v[180:183], v[204:207], v[76:79]
	v_mfma_f32_16x16x32_bf16 v[68:71], v[172:175], v[212:215], v[68:71]
	v_mfma_f32_16x16x32_bf16 v[64:67], v[180:183], v[212:215], v[64:67]
	v_mfma_f32_16x16x32_bf16 v[116:119], v[176:179], v[192:195], v[116:119]
	v_mfma_f32_16x16x32_bf16 v[108:111], v[184:187], v[192:195], v[108:111]
	v_mfma_f32_16x16x32_bf16 v[100:103], v[176:179], v[200:203], v[100:103]
	v_mfma_f32_16x16x32_bf16 v[92:95], v[184:187], v[200:203], v[92:95]
	v_mfma_f32_16x16x32_bf16 v[84:87], v[176:179], v[208:211], v[84:87]
	v_mfma_f32_16x16x32_bf16 v[76:79], v[184:187], v[208:211], v[76:79]
	v_mfma_f32_16x16x32_bf16 v[68:71], v[176:179], v[216:219], v[68:71]
	v_mfma_f32_16x16x32_bf16 v[64:67], v[184:187], v[216:219], v[64:67]
	s_barrier
	s_setprio 0
	s_add_i32 s65, s58, s24
	s_mov_b32 m0, s65
	ds_read_b128 v[188:191], v154 offset:16384
	ds_read_b128 v[192:195], v154 offset:17408
	ds_read_b128 v[196:199], v154 offset:18432
	ds_read_b128 v[200:203], v154 offset:19456
	ds_read_b128 v[204:207], v154 offset:20480
	global_load_lds_dwordx4 v132, s[40:41]
	s_add_i32 m0, s65, 0x2000
	s_add_u32 s66, s40, 0x100000
	s_mov_b64 s[98:99], s[40:41]
	s_addc_u32 s67, s41, 0
	s_add_i32 s65, s59, s24
	global_load_lds_dwordx4 v128, s[98:99]
	s_mov_b32 m0, s65
	s_mov_b64 s[100:101], s[56:57]
	global_load_lds_dwordx4 v132, s[66:67]
	s_add_i32 m0, s65, 0x2000
	ds_read_b128 v[208:211], v154 offset:21504
	global_load_lds_dwordx4 v128, s[66:67]
	s_mov_b64 s[100:101], s[56:57]
	s_mov_b32 m0, s29
	ds_read_b128 v[212:215], v154 offset:22528
	global_load_lds_dwordx4 v134, s[100:101]
	s_mov_b32 m0, s30
	ds_read_b128 v[216:219], v154 offset:23552
	global_load_lds_dwordx4 v130, s[100:101]
	s_waitcnt vmcnt(8) lgkmcnt(0)
	s_setprio 1
	s_barrier
	v_mfma_f32_16x16x32_bf16 v[60:63], v[156:159], v[188:191], v[60:63]
	v_mfma_f32_16x16x32_bf16 v[56:59], v[164:167], v[188:191], v[56:59]
	v_mfma_f32_16x16x32_bf16 v[52:55], v[156:159], v[196:199], v[52:55]
	v_mfma_f32_16x16x32_bf16 v[44:47], v[164:167], v[196:199], v[44:47]
	v_mfma_f32_16x16x32_bf16 v[36:39], v[156:159], v[204:207], v[36:39]
	v_mfma_f32_16x16x32_bf16 v[28:31], v[164:167], v[204:207], v[28:31]
	v_mfma_f32_16x16x32_bf16 v[20:23], v[156:159], v[212:215], v[20:23]
	v_mfma_f32_16x16x32_bf16 v[12:15], v[164:167], v[212:215], v[12:15]
	v_mfma_f32_16x16x32_bf16 v[60:63], v[160:163], v[192:195], v[60:63]
	v_mfma_f32_16x16x32_bf16 v[56:59], v[168:171], v[192:195], v[56:59]
	v_mfma_f32_16x16x32_bf16 v[52:55], v[160:163], v[200:203], v[52:55]
	v_mfma_f32_16x16x32_bf16 v[44:47], v[168:171], v[200:203], v[44:47]
	v_mfma_f32_16x16x32_bf16 v[36:39], v[160:163], v[208:211], v[36:39]
	v_mfma_f32_16x16x32_bf16 v[28:31], v[168:171], v[208:211], v[28:31]
	v_mfma_f32_16x16x32_bf16 v[20:23], v[160:163], v[216:219], v[20:23]
	v_mfma_f32_16x16x32_bf16 v[12:15], v[168:171], v[216:219], v[12:15]
	v_mfma_f32_16x16x32_bf16 v[48:51], v[172:175], v[188:191], v[48:51]
	v_mfma_f32_16x16x32_bf16 v[40:43], v[180:183], v[188:191], v[40:43]
	v_mfma_f32_16x16x32_bf16 v[32:35], v[172:175], v[196:199], v[32:35]
	v_mfma_f32_16x16x32_bf16 v[24:27], v[180:183], v[196:199], v[24:27]
	v_mfma_f32_16x16x32_bf16 v[16:19], v[172:175], v[204:207], v[16:19]
	v_mfma_f32_16x16x32_bf16 v[8:11], v[180:183], v[204:207], v[8:11]
	v_mfma_f32_16x16x32_bf16 v[4:7], v[172:175], v[212:215], v[4:7]
	v_mfma_f32_16x16x32_bf16 v[0:3], v[180:183], v[212:215], v[0:3]
	v_mfma_f32_16x16x32_bf16 v[48:51], v[176:179], v[192:195], v[48:51]
	v_mfma_f32_16x16x32_bf16 v[40:43], v[184:187], v[192:195], v[40:43]
	v_mfma_f32_16x16x32_bf16 v[32:35], v[176:179], v[200:203], v[32:35]
	v_mfma_f32_16x16x32_bf16 v[24:27], v[184:187], v[200:203], v[24:27]
	v_mfma_f32_16x16x32_bf16 v[16:19], v[176:179], v[208:211], v[16:19]
	v_mfma_f32_16x16x32_bf16 v[8:11], v[184:187], v[208:211], v[8:11]
	v_mfma_f32_16x16x32_bf16 v[4:7], v[176:179], v[216:219], v[4:7]
	v_mfma_f32_16x16x32_bf16 v[0:3], v[184:187], v[216:219], v[0:3]
	s_barrier
	s_setprio 0
	s_add_i32 s65, 0, 0x18000
	s_add_i32 s66, 0, 0x1c000
	ds_read_b128 v[156:159], v152 offset:32768
	ds_read_b128 v[160:163], v152 offset:33792
	ds_read_b128 v[164:167], v152 offset:34816
	ds_read_b128 v[168:171], v152 offset:35840
	ds_read_b128 v[172:175], v153 offset:32768
	ds_read_b128 v[176:179], v153 offset:33792
	ds_read_b128 v[180:183], v153 offset:34816
	ds_read_b128 v[184:187], v153 offset:35840
	s_add_u32 s56, s56, 0x100000
	s_addc_u32 s57, s57, 0
	s_mov_b32 m0, s31
	ds_read_b128 v[188:191], v154 offset:32768
	ds_read_b128 v[192:195], v154 offset:33792
	ds_read_b128 v[196:199], v154 offset:34816
	ds_read_b128 v[200:203], v154 offset:35840
	ds_read_b128 v[204:207], v154 offset:36864
	ds_read_b128 v[208:211], v154 offset:37888
	ds_read_b128 v[212:215], v154 offset:38912
	global_load_lds_dwordx4 v134, s[56:57]
	s_mov_b32 m0, s33
	ds_read_b128 v[216:219], v154 offset:39936
	global_load_lds_dwordx4 v130, s[56:57]
	s_waitcnt vmcnt(8) lgkmcnt(0)
	s_setprio 1
	s_barrier
	v_mfma_f32_16x16x32_bf16 v[124:127], v[156:159], v[188:191], v[124:127]
	v_mfma_f32_16x16x32_bf16 v[120:123], v[164:167], v[188:191], v[120:123]
	v_mfma_f32_16x16x32_bf16 v[112:115], v[156:159], v[196:199], v[112:115]
	v_mfma_f32_16x16x32_bf16 v[104:107], v[164:167], v[196:199], v[104:107]
	v_mfma_f32_16x16x32_bf16 v[96:99], v[156:159], v[204:207], v[96:99]
	v_mfma_f32_16x16x32_bf16 v[88:91], v[164:167], v[204:207], v[88:91]
	v_mfma_f32_16x16x32_bf16 v[80:83], v[156:159], v[212:215], v[80:83]
	v_mfma_f32_16x16x32_bf16 v[72:75], v[164:167], v[212:215], v[72:75]
	v_mfma_f32_16x16x32_bf16 v[124:127], v[160:163], v[192:195], v[124:127]
	v_mfma_f32_16x16x32_bf16 v[120:123], v[168:171], v[192:195], v[120:123]
	v_mfma_f32_16x16x32_bf16 v[112:115], v[160:163], v[200:203], v[112:115]
	v_mfma_f32_16x16x32_bf16 v[104:107], v[168:171], v[200:203], v[104:107]
	v_mfma_f32_16x16x32_bf16 v[96:99], v[160:163], v[208:211], v[96:99]
	v_mfma_f32_16x16x32_bf16 v[88:91], v[168:171], v[208:211], v[88:91]
	v_mfma_f32_16x16x32_bf16 v[80:83], v[160:163], v[216:219], v[80:83]
	v_mfma_f32_16x16x32_bf16 v[72:75], v[168:171], v[216:219], v[72:75]
	v_mfma_f32_16x16x32_bf16 v[116:119], v[172:175], v[188:191], v[116:119]
	v_mfma_f32_16x16x32_bf16 v[108:111], v[180:183], v[188:191], v[108:111]
	v_mfma_f32_16x16x32_bf16 v[100:103], v[172:175], v[196:199], v[100:103]
	v_mfma_f32_16x16x32_bf16 v[92:95], v[180:183], v[196:199], v[92:95]
	v_mfma_f32_16x16x32_bf16 v[84:87], v[172:175], v[204:207], v[84:87]
	v_mfma_f32_16x16x32_bf16 v[76:79], v[180:183], v[204:207], v[76:79]
	v_mfma_f32_16x16x32_bf16 v[68:71], v[172:175], v[212:215], v[68:71]
	v_mfma_f32_16x16x32_bf16 v[64:67], v[180:183], v[212:215], v[64:67]
	v_mfma_f32_16x16x32_bf16 v[116:119], v[176:179], v[192:195], v[116:119]
	v_mfma_f32_16x16x32_bf16 v[108:111], v[184:187], v[192:195], v[108:111]
	v_mfma_f32_16x16x32_bf16 v[100:103], v[176:179], v[200:203], v[100:103]
	v_mfma_f32_16x16x32_bf16 v[92:95], v[184:187], v[200:203], v[92:95]
	v_mfma_f32_16x16x32_bf16 v[84:87], v[176:179], v[208:211], v[84:87]
	v_mfma_f32_16x16x32_bf16 v[76:79], v[184:187], v[208:211], v[76:79]
	v_mfma_f32_16x16x32_bf16 v[68:71], v[176:179], v[216:219], v[68:71]
	v_mfma_f32_16x16x32_bf16 v[64:67], v[184:187], v[216:219], v[64:67]
	s_barrier
	s_setprio 0
	s_add_i32 s56, s65, s24
	s_add_i32 m0, s56, -128
	ds_read_b128 v[188:191], v154 offset:49152
	ds_read_b128 v[192:195], v154 offset:50176
	ds_read_b128 v[196:199], v154 offset:51200
	ds_read_b128 v[200:203], v154 offset:52224
	global_load_lds_dwordx4 v132, s[40:41] offset:128
	s_add_i32 m0, s56, 8064
	s_add_u32 s40, s40, 0x100080
	s_addc_u32 s41, s41, 0
	s_add_i32 s56, s66, s24
	global_load_lds_dwordx4 v128, s[98:99] offset:128
	s_mov_b32 m0, s56
	ds_read_b128 v[204:207], v154 offset:53248
	global_load_lds_dwordx4 v132, s[40:41]
	s_add_i32 m0, s56, 0x2000
	ds_read_b128 v[208:211], v154 offset:54272
	global_load_lds_dwordx4 v128, s[40:41]
	s_add_i32 m0, s54, -128
	ds_read_b128 v[212:215], v154 offset:55296
	global_load_lds_dwordx4 v134, s[100:101] offset:128
	s_add_i32 m0, s55, -128
	ds_read_b128 v[216:219], v154 offset:56320
	global_load_lds_dwordx4 v130, s[100:101] offset:128
	s_waitcnt vmcnt(8) lgkmcnt(0)
	s_setprio 1
	s_barrier
	v_mfma_f32_16x16x32_bf16 v[60:63], v[156:159], v[188:191], v[60:63]
	v_mfma_f32_16x16x32_bf16 v[56:59], v[164:167], v[188:191], v[56:59]
	v_mfma_f32_16x16x32_bf16 v[52:55], v[156:159], v[196:199], v[52:55]
	v_mfma_f32_16x16x32_bf16 v[44:47], v[164:167], v[196:199], v[44:47]
	v_mfma_f32_16x16x32_bf16 v[36:39], v[156:159], v[204:207], v[36:39]
	v_mfma_f32_16x16x32_bf16 v[28:31], v[164:167], v[204:207], v[28:31]
	v_mfma_f32_16x16x32_bf16 v[20:23], v[156:159], v[212:215], v[20:23]
	v_mfma_f32_16x16x32_bf16 v[12:15], v[164:167], v[212:215], v[12:15]
	v_mfma_f32_16x16x32_bf16 v[60:63], v[160:163], v[192:195], v[60:63]
	v_mfma_f32_16x16x32_bf16 v[56:59], v[168:171], v[192:195], v[56:59]
	v_mfma_f32_16x16x32_bf16 v[52:55], v[160:163], v[200:203], v[52:55]
	v_mfma_f32_16x16x32_bf16 v[44:47], v[168:171], v[200:203], v[44:47]
	v_mfma_f32_16x16x32_bf16 v[36:39], v[160:163], v[208:211], v[36:39]
	v_mfma_f32_16x16x32_bf16 v[28:31], v[168:171], v[208:211], v[28:31]
	v_mfma_f32_16x16x32_bf16 v[20:23], v[160:163], v[216:219], v[20:23]
	v_mfma_f32_16x16x32_bf16 v[12:15], v[168:171], v[216:219], v[12:15]
	v_mfma_f32_16x16x32_bf16 v[48:51], v[172:175], v[188:191], v[48:51]
	v_mfma_f32_16x16x32_bf16 v[40:43], v[180:183], v[188:191], v[40:43]
	v_mfma_f32_16x16x32_bf16 v[32:35], v[172:175], v[196:199], v[32:35]
	v_mfma_f32_16x16x32_bf16 v[24:27], v[180:183], v[196:199], v[24:27]
	v_mfma_f32_16x16x32_bf16 v[16:19], v[172:175], v[204:207], v[16:19]
	v_mfma_f32_16x16x32_bf16 v[8:11], v[180:183], v[204:207], v[8:11]
	v_mfma_f32_16x16x32_bf16 v[4:7], v[172:175], v[212:215], v[4:7]
	v_mfma_f32_16x16x32_bf16 v[0:3], v[180:183], v[212:215], v[0:3]
	v_mfma_f32_16x16x32_bf16 v[48:51], v[176:179], v[192:195], v[48:51]
	v_mfma_f32_16x16x32_bf16 v[40:43], v[184:187], v[192:195], v[40:43]
	v_mfma_f32_16x16x32_bf16 v[32:35], v[176:179], v[200:203], v[32:35]
	v_mfma_f32_16x16x32_bf16 v[24:27], v[184:187], v[200:203], v[24:27]
	v_mfma_f32_16x16x32_bf16 v[16:19], v[176:179], v[208:211], v[16:19]
	v_mfma_f32_16x16x32_bf16 v[8:11], v[184:187], v[208:211], v[8:11]
	v_mfma_f32_16x16x32_bf16 v[4:7], v[176:179], v[216:219], v[4:7]
	v_mfma_f32_16x16x32_bf16 v[0:3], v[184:187], v[216:219], v[0:3]
	s_barrier
	s_setprio 0
	s_add_i32 s64, s64, 2
	s_add_u32 s38, s38, 0x100
	s_addc_u32 s39, s39, 0
	s_add_u32 s62, s62, 0x100
	s_addc_u32 s63, s63, 0
	s_cmp_gt_u32 s64, 61
	s_cbranch_scc0 .LBB0_394
	s_and_b64 vcc, exec, s[12:13]
	s_cbranch_vccz .LBB0_397
	s_barrier

.LBB0_622:
	ds_read_b128 v[152:155], v149
	ds_read_b128 v[156:159], v149 offset:1024
	ds_read_b128 v[160:163], v149 offset:2048
	ds_read_b128 v[164:167], v149 offset:3072
	ds_read_b128 v[168:171], v150
	ds_read_b128 v[172:175], v150 offset:1024
	ds_read_b128 v[176:179], v150 offset:2048
	ds_read_b128 v[180:183], v150 offset:3072
	s_add_u32 s42, s40, 0xfff00080
	s_addc_u32 s43, s41, -1
	s_cmp_eq_u32 s61, 60
	s_cselect_b32 s45, s25, s43
	s_cselect_b32 s44, s57, s42
	s_cselect_b32 s43, s23, s60
	s_cselect_b32 s42, s58, s59
	s_add_i32 m0, s31, 0xc000
	ds_read_b128 v[184:187], v151
	ds_read_b128 v[188:191], v151 offset:1024
	ds_read_b128 v[192:195], v151 offset:2048
	ds_read_b128 v[196:199], v151 offset:3072
	ds_read_b128 v[200:203], v151 offset:4096
	ds_read_b128 v[204:207], v151 offset:5120
	ds_read_b128 v[208:211], v151 offset:6144
	global_load_lds_dwordx4 v136, s[40:41]
	s_add_i32 m0, s31, 0xe000
	ds_read_b128 v[212:215], v151 offset:7168
	global_load_lds_dwordx4 v138, s[40:41]
	s_waitcnt vmcnt(8) lgkmcnt(0)
	s_setprio 1
	s_barrier
	v_mfma_f32_16x16x32_bf16 v[124:127], v[152:155], v[184:187], v[124:127]
	v_mfma_f32_16x16x32_bf16 v[120:123], v[160:163], v[184:187], v[120:123]
	v_mfma_f32_16x16x32_bf16 v[116:119], v[152:155], v[192:195], v[116:119]
	v_mfma_f32_16x16x32_bf16 v[108:111], v[160:163], v[192:195], v[108:111]
	v_mfma_f32_16x16x32_bf16 v[100:103], v[152:155], v[200:203], v[100:103]
	v_mfma_f32_16x16x32_bf16 v[92:95], v[160:163], v[200:203], v[92:95]
	v_mfma_f32_16x16x32_bf16 v[84:87], v[152:155], v[208:211], v[84:87]
	v_mfma_f32_16x16x32_bf16 v[76:79], v[160:163], v[208:211], v[76:79]
	v_mfma_f32_16x16x32_bf16 v[124:127], v[156:159], v[188:191], v[124:127]
	v_mfma_f32_16x16x32_bf16 v[120:123], v[164:167], v[188:191], v[120:123]
	v_mfma_f32_16x16x32_bf16 v[116:119], v[156:159], v[196:199], v[116:119]
	v_mfma_f32_16x16x32_bf16 v[108:111], v[164:167], v[196:199], v[108:111]
	v_mfma_f32_16x16x32_bf16 v[100:103], v[156:159], v[204:207], v[100:103]
	v_mfma_f32_16x16x32_bf16 v[92:95], v[164:167], v[204:207], v[92:95]
	v_mfma_f32_16x16x32_bf16 v[84:87], v[156:159], v[212:215], v[84:87]
	v_mfma_f32_16x16x32_bf16 v[76:79], v[164:167], v[212:215], v[76:79]
	v_mfma_f32_16x16x32_bf16 v[112:115], v[168:171], v[184:187], v[112:115]
	v_mfma_f32_16x16x32_bf16 v[104:107], v[176:179], v[184:187], v[104:107]
	v_mfma_f32_16x16x32_bf16 v[96:99], v[168:171], v[192:195], v[96:99]
	v_mfma_f32_16x16x32_bf16 v[88:91], v[176:179], v[192:195], v[88:91]
	v_mfma_f32_16x16x32_bf16 v[80:83], v[168:171], v[200:203], v[80:83]
	v_mfma_f32_16x16x32_bf16 v[72:75], v[176:179], v[200:203], v[72:75]
	v_mfma_f32_16x16x32_bf16 v[68:71], v[168:171], v[208:211], v[68:71]
	v_mfma_f32_16x16x32_bf16 v[64:67], v[176:179], v[208:211], v[64:67]
	v_mfma_f32_16x16x32_bf16 v[112:115], v[172:175], v[188:191], v[112:115]
	v_mfma_f32_16x16x32_bf16 v[104:107], v[180:183], v[188:191], v[104:107]
	v_mfma_f32_16x16x32_bf16 v[96:99], v[172:175], v[196:199], v[96:99]
	v_mfma_f32_16x16x32_bf16 v[88:91], v[180:183], v[196:199], v[88:91]
	v_mfma_f32_16x16x32_bf16 v[80:83], v[172:175], v[204:207], v[80:83]
	v_mfma_f32_16x16x32_bf16 v[72:75], v[180:183], v[204:207], v[72:75]
	v_mfma_f32_16x16x32_bf16 v[68:71], v[172:175], v[212:215], v[68:71]
	v_mfma_f32_16x16x32_bf16 v[64:67], v[180:183], v[212:215], v[64:67]
	s_barrier
	s_setprio 0
	s_add_i32 s62, s50, s29
	s_mov_b32 m0, s62
	ds_read_b128 v[184:187], v151 offset:16384
	ds_read_b128 v[188:191], v151 offset:17408
	ds_read_b128 v[192:195], v151 offset:18432
	ds_read_b128 v[196:199], v151 offset:19456
	ds_read_b128 v[200:203], v151 offset:20480
	global_load_lds_dwordx4 v132, s[42:43]
	s_add_i32 m0, s62, 0x2000
	s_add_u32 s62, s42, 0x100000
	s_mov_b64 s[98:99], s[42:43]
	s_addc_u32 s63, s43, 0
	s_add_i32 s64, s51, s29
	global_load_lds_dwordx4 v128, s[98:99]
	s_mov_b32 m0, s64
	s_mov_b64 s[100:101], s[44:45]
	global_load_lds_dwordx4 v132, s[62:63]
	s_add_i32 m0, s64, 0x2000
	ds_read_b128 v[204:207], v151 offset:21504
	global_load_lds_dwordx4 v128, s[62:63]
	s_mov_b64 s[100:101], s[44:45]
	s_mov_b32 m0, s31
	ds_read_b128 v[208:211], v151 offset:22528
	global_load_lds_dwordx4 v134, s[100:101]
	s_mov_b32 m0, s33
	ds_read_b128 v[212:215], v151 offset:23552
	global_load_lds_dwordx4 v130, s[100:101]
	s_waitcnt vmcnt(8) lgkmcnt(0)
	s_setprio 1
	s_barrier
	v_mfma_f32_16x16x32_bf16 v[60:63], v[152:155], v[184:187], v[60:63]
	v_mfma_f32_16x16x32_bf16 v[56:59], v[160:163], v[184:187], v[56:59]
	v_mfma_f32_16x16x32_bf16 v[52:55], v[152:155], v[192:195], v[52:55]
	v_mfma_f32_16x16x32_bf16 v[44:47], v[160:163], v[192:195], v[44:47]
	v_mfma_f32_16x16x32_bf16 v[36:39], v[152:155], v[200:203], v[36:39]
	v_mfma_f32_16x16x32_bf16 v[28:31], v[160:163], v[200:203], v[28:31]
	v_mfma_f32_16x16x32_bf16 v[20:23], v[152:155], v[208:211], v[20:23]
	v_mfma_f32_16x16x32_bf16 v[12:15], v[160:163], v[208:211], v[12:15]
	v_mfma_f32_16x16x32_bf16 v[60:63], v[156:159], v[188:191], v[60:63]
	v_mfma_f32_16x16x32_bf16 v[56:59], v[164:167], v[188:191], v[56:59]
	v_mfma_f32_16x16x32_bf16 v[52:55], v[156:159], v[196:199], v[52:55]
	v_mfma_f32_16x16x32_bf16 v[44:47], v[164:167], v[196:199], v[44:47]
	v_mfma_f32_16x16x32_bf16 v[36:39], v[156:159], v[204:207], v[36:39]
	v_mfma_f32_16x16x32_bf16 v[28:31], v[164:167], v[204:207], v[28:31]
	v_mfma_f32_16x16x32_bf16 v[20:23], v[156:159], v[212:215], v[20:23]
	v_mfma_f32_16x16x32_bf16 v[12:15], v[164:167], v[212:215], v[12:15]
	v_mfma_f32_16x16x32_bf16 v[48:51], v[168:171], v[184:187], v[48:51]
	v_mfma_f32_16x16x32_bf16 v[40:43], v[176:179], v[184:187], v[40:43]
	v_mfma_f32_16x16x32_bf16 v[32:35], v[168:171], v[192:195], v[32:35]
	v_mfma_f32_16x16x32_bf16 v[24:27], v[176:179], v[192:195], v[24:27]
	v_mfma_f32_16x16x32_bf16 v[16:19], v[168:171], v[200:203], v[16:19]
	v_mfma_f32_16x16x32_bf16 v[8:11], v[176:179], v[200:203], v[8:11]
	v_mfma_f32_16x16x32_bf16 v[4:7], v[168:171], v[208:211], v[4:7]
	v_mfma_f32_16x16x32_bf16 v[0:3], v[176:179], v[208:211], v[0:3]
	v_mfma_f32_16x16x32_bf16 v[48:51], v[172:175], v[188:191], v[48:51]
	v_mfma_f32_16x16x32_bf16 v[40:43], v[180:183], v[188:191], v[40:43]
	v_mfma_f32_16x16x32_bf16 v[32:35], v[172:175], v[196:199], v[32:35]
	v_mfma_f32_16x16x32_bf16 v[24:27], v[180:183], v[196:199], v[24:27]
	v_mfma_f32_16x16x32_bf16 v[16:19], v[172:175], v[204:207], v[16:19]
	v_mfma_f32_16x16x32_bf16 v[8:11], v[180:183], v[204:207], v[8:11]
	v_mfma_f32_16x16x32_bf16 v[4:7], v[172:175], v[212:215], v[4:7]
	v_mfma_f32_16x16x32_bf16 v[0:3], v[180:183], v[212:215], v[0:3]
	s_barrier
	s_setprio 0
	s_add_i32 s62, 0, 0x18000
	s_add_i32 s63, 0, 0x1c000
	ds_read_b128 v[152:155], v149 offset:32768
	ds_read_b128 v[156:159], v149 offset:33792
	ds_read_b128 v[160:163], v149 offset:34816
	ds_read_b128 v[164:167], v149 offset:35840
	ds_read_b128 v[168:171], v150 offset:32768
	ds_read_b128 v[172:175], v150 offset:33792
	ds_read_b128 v[176:179], v150 offset:34816
	ds_read_b128 v[180:183], v150 offset:35840
	s_add_u32 s44, s44, 0x100000
	s_addc_u32 s45, s45, 0
	s_mov_b32 m0, s35
	ds_read_b128 v[184:187], v151 offset:32768
	ds_read_b128 v[188:191], v151 offset:33792
	ds_read_b128 v[192:195], v151 offset:34816
	ds_read_b128 v[196:199], v151 offset:35840
	ds_read_b128 v[200:203], v151 offset:36864
	ds_read_b128 v[204:207], v151 offset:37888
	ds_read_b128 v[208:211], v151 offset:38912
	global_load_lds_dwordx4 v134, s[44:45]
	s_mov_b32 m0, s39
	ds_read_b128 v[212:215], v151 offset:39936
	global_load_lds_dwordx4 v130, s[44:45]
	s_waitcnt vmcnt(8) lgkmcnt(0)
	s_setprio 1
	s_barrier
	v_mfma_f32_16x16x32_bf16 v[124:127], v[152:155], v[184:187], v[124:127]
	v_mfma_f32_16x16x32_bf16 v[120:123], v[160:163], v[184:187], v[120:123]
	v_mfma_f32_16x16x32_bf16 v[116:119], v[152:155], v[192:195], v[116:119]
	v_mfma_f32_16x16x32_bf16 v[108:111], v[160:163], v[192:195], v[108:111]
	v_mfma_f32_16x16x32_bf16 v[100:103], v[152:155], v[200:203], v[100:103]
	v_mfma_f32_16x16x32_bf16 v[92:95], v[160:163], v[200:203], v[92:95]
	v_mfma_f32_16x16x32_bf16 v[84:87], v[152:155], v[208:211], v[84:87]
	v_mfma_f32_16x16x32_bf16 v[76:79], v[160:163], v[208:211], v[76:79]
	v_mfma_f32_16x16x32_bf16 v[124:127], v[156:159], v[188:191], v[124:127]
	v_mfma_f32_16x16x32_bf16 v[120:123], v[164:167], v[188:191], v[120:123]
	v_mfma_f32_16x16x32_bf16 v[116:119], v[156:159], v[196:199], v[116:119]
	v_mfma_f32_16x16x32_bf16 v[108:111], v[164:167], v[196:199], v[108:111]
	v_mfma_f32_16x16x32_bf16 v[100:103], v[156:159], v[204:207], v[100:103]
	v_mfma_f32_16x16x32_bf16 v[92:95], v[164:167], v[204:207], v[92:95]
	v_mfma_f32_16x16x32_bf16 v[84:87], v[156:159], v[212:215], v[84:87]
	v_mfma_f32_16x16x32_bf16 v[76:79], v[164:167], v[212:215], v[76:79]
	v_mfma_f32_16x16x32_bf16 v[112:115], v[168:171], v[184:187], v[112:115]
	v_mfma_f32_16x16x32_bf16 v[104:107], v[176:179], v[184:187], v[104:107]
	v_mfma_f32_16x16x32_bf16 v[96:99], v[168:171], v[192:195], v[96:99]
	v_mfma_f32_16x16x32_bf16 v[88:91], v[176:179], v[192:195], v[88:91]
	v_mfma_f32_16x16x32_bf16 v[80:83], v[168:171], v[200:203], v[80:83]
	v_mfma_f32_16x16x32_bf16 v[72:75], v[176:179], v[200:203], v[72:75]
	v_mfma_f32_16x16x32_bf16 v[68:71], v[168:171], v[208:211], v[68:71]
	v_mfma_f32_16x16x32_bf16 v[64:67], v[176:179], v[208:211], v[64:67]
	v_mfma_f32_16x16x32_bf16 v[112:115], v[172:175], v[188:191], v[112:115]
	v_mfma_f32_16x16x32_bf16 v[104:107], v[180:183], v[188:191], v[104:107]
	v_mfma_f32_16x16x32_bf16 v[96:99], v[172:175], v[196:199], v[96:99]
	v_mfma_f32_16x16x32_bf16 v[88:91], v[180:183], v[196:199], v[88:91]
	v_mfma_f32_16x16x32_bf16 v[80:83], v[172:175], v[204:207], v[80:83]
	v_mfma_f32_16x16x32_bf16 v[72:75], v[180:183], v[204:207], v[72:75]
	v_mfma_f32_16x16x32_bf16 v[68:71], v[172:175], v[212:215], v[68:71]
	v_mfma_f32_16x16x32_bf16 v[64:67], v[180:183], v[212:215], v[64:67]
	s_barrier
	s_setprio 0
	s_add_i32 s44, s62, s29
	s_add_i32 m0, s44, -128
	ds_read_b128 v[184:187], v151 offset:49152
	ds_read_b128 v[188:191], v151 offset:50176
	ds_read_b128 v[192:195], v151 offset:51200
	ds_read_b128 v[196:199], v151 offset:52224
	global_load_lds_dwordx4 v132, s[42:43] offset:128
	s_add_i32 m0, s44, 8064
	s_add_u32 s42, s42, 0x100080
	s_addc_u32 s43, s43, 0
	s_add_i32 s44, s63, s29
	global_load_lds_dwordx4 v128, s[98:99] offset:128
	s_mov_b32 m0, s44
	ds_read_b128 v[200:203], v151 offset:53248
	global_load_lds_dwordx4 v132, s[42:43]
	s_add_i32 m0, s44, 0x2000
	ds_read_b128 v[204:207], v151 offset:54272
	global_load_lds_dwordx4 v128, s[42:43]
	s_add_i32 m0, s48, -128
	ds_read_b128 v[208:211], v151 offset:55296
	global_load_lds_dwordx4 v134, s[100:101] offset:128
	s_add_i32 m0, s49, -128
	ds_read_b128 v[212:215], v151 offset:56320
	global_load_lds_dwordx4 v130, s[100:101] offset:128
	s_waitcnt vmcnt(8) lgkmcnt(0)
	s_setprio 1
	s_barrier
	v_mfma_f32_16x16x32_bf16 v[60:63], v[152:155], v[184:187], v[60:63]
	v_mfma_f32_16x16x32_bf16 v[56:59], v[160:163], v[184:187], v[56:59]
	v_mfma_f32_16x16x32_bf16 v[52:55], v[152:155], v[192:195], v[52:55]
	v_mfma_f32_16x16x32_bf16 v[44:47], v[160:163], v[192:195], v[44:47]
	v_mfma_f32_16x16x32_bf16 v[36:39], v[152:155], v[200:203], v[36:39]
	v_mfma_f32_16x16x32_bf16 v[28:31], v[160:163], v[200:203], v[28:31]
	v_mfma_f32_16x16x32_bf16 v[20:23], v[152:155], v[208:211], v[20:23]
	v_mfma_f32_16x16x32_bf16 v[12:15], v[160:163], v[208:211], v[12:15]
	v_mfma_f32_16x16x32_bf16 v[60:63], v[156:159], v[188:191], v[60:63]
	v_mfma_f32_16x16x32_bf16 v[56:59], v[164:167], v[188:191], v[56:59]
	v_mfma_f32_16x16x32_bf16 v[52:55], v[156:159], v[196:199], v[52:55]
	v_mfma_f32_16x16x32_bf16 v[44:47], v[164:167], v[196:199], v[44:47]
	v_mfma_f32_16x16x32_bf16 v[36:39], v[156:159], v[204:207], v[36:39]
	v_mfma_f32_16x16x32_bf16 v[28:31], v[164:167], v[204:207], v[28:31]
	v_mfma_f32_16x16x32_bf16 v[20:23], v[156:159], v[212:215], v[20:23]
	v_mfma_f32_16x16x32_bf16 v[12:15], v[164:167], v[212:215], v[12:15]
	v_mfma_f32_16x16x32_bf16 v[48:51], v[168:171], v[184:187], v[48:51]
	v_mfma_f32_16x16x32_bf16 v[40:43], v[176:179], v[184:187], v[40:43]
	v_mfma_f32_16x16x32_bf16 v[32:35], v[168:171], v[192:195], v[32:35]
	v_mfma_f32_16x16x32_bf16 v[24:27], v[176:179], v[192:195], v[24:27]
	v_mfma_f32_16x16x32_bf16 v[16:19], v[168:171], v[200:203], v[16:19]
	v_mfma_f32_16x16x32_bf16 v[8:11], v[176:179], v[200:203], v[8:11]
	v_mfma_f32_16x16x32_bf16 v[4:7], v[168:171], v[208:211], v[4:7]
	v_mfma_f32_16x16x32_bf16 v[0:3], v[176:179], v[208:211], v[0:3]
	v_mfma_f32_16x16x32_bf16 v[48:51], v[172:175], v[188:191], v[48:51]
	v_mfma_f32_16x16x32_bf16 v[40:43], v[180:183], v[188:191], v[40:43]
	v_mfma_f32_16x16x32_bf16 v[32:35], v[172:175], v[196:199], v[32:35]
	v_mfma_f32_16x16x32_bf16 v[24:27], v[180:183], v[196:199], v[24:27]
	v_mfma_f32_16x16x32_bf16 v[16:19], v[172:175], v[204:207], v[16:19]
	v_mfma_f32_16x16x32_bf16 v[8:11], v[180:183], v[204:207], v[8:11]
	v_mfma_f32_16x16x32_bf16 v[4:7], v[172:175], v[212:215], v[4:7]
	v_mfma_f32_16x16x32_bf16 v[0:3], v[180:183], v[212:215], v[0:3]
	s_barrier
	s_setprio 0
	s_add_i32 s61, s61, 2
	s_add_u32 s40, s40, 0x100
	s_addc_u32 s41, s41, 0
	s_add_u32 s59, s59, 0x100
	s_addc_u32 s60, s60, 0
	s_cmp_gt_u32 s61, 61
	s_cbranch_scc0 .LBB0_622
	s_and_b64 vcc, exec, s[10:11]
	s_cbranch_vccz .LBB0_625
	s_barrier

.LBB0_773:
	ds_read_b128 v[144:147], v155
	ds_read_b128 v[148:151], v155 offset:1024
	ds_read_b128 v[158:161], v155 offset:2048
	ds_read_b128 v[162:165], v155 offset:3072
	ds_read_b128 v[166:169], v156
	ds_read_b128 v[170:173], v156 offset:1024
	ds_read_b128 v[174:177], v156 offset:2048
	ds_read_b128 v[178:181], v156 offset:3072
	s_add_u32 s36, s30, 0xfff80080
	s_addc_u32 s37, s31, -1
	s_cmp_eq_u32 s52, 28
	s_cselect_b32 s39, s23, s37
	s_cselect_b32 s38, s48, s36
	s_cselect_b32 s37, s21, s51
	s_cselect_b32 s36, s49, s50
	s_add_i32 m0, s17, 0xc000
	ds_read_b128 v[182:185], v157
	ds_read_b128 v[186:189], v157 offset:1024
	ds_read_b128 v[190:193], v157 offset:2048
	ds_read_b128 v[194:197], v157 offset:3072
	ds_read_b128 v[198:201], v157 offset:4096
	ds_read_b128 v[202:205], v157 offset:5120
	ds_read_b128 v[206:209], v157 offset:6144
	global_load_lds_dwordx4 v136, s[30:31]
	s_add_i32 m0, s17, 0xe000
	ds_read_b128 v[210:213], v157 offset:7168
	global_load_lds_dwordx4 v138, s[30:31]
	s_waitcnt vmcnt(8) lgkmcnt(0)
	s_setprio 1
	s_barrier
	v_mfma_i32_16x16x64_i8 v[124:127], v[144:147], v[182:185], v[124:127]
	v_mfma_i32_16x16x64_i8 v[116:119], v[158:161], v[182:185], v[116:119]
	v_mfma_i32_16x16x64_i8 v[108:111], v[144:147], v[190:193], v[108:111]
	v_mfma_i32_16x16x64_i8 v[100:103], v[158:161], v[190:193], v[100:103]
	v_mfma_i32_16x16x64_i8 v[92:95], v[144:147], v[198:201], v[92:95]
	v_mfma_i32_16x16x64_i8 v[84:87], v[158:161], v[198:201], v[84:87]
	v_mfma_i32_16x16x64_i8 v[76:79], v[144:147], v[206:209], v[76:79]
	v_mfma_i32_16x16x64_i8 v[68:71], v[158:161], v[206:209], v[68:71]
	v_mfma_i32_16x16x64_i8 v[124:127], v[148:151], v[186:189], v[124:127]
	v_mfma_i32_16x16x64_i8 v[116:119], v[162:165], v[186:189], v[116:119]
	v_mfma_i32_16x16x64_i8 v[108:111], v[148:151], v[194:197], v[108:111]
	v_mfma_i32_16x16x64_i8 v[100:103], v[162:165], v[194:197], v[100:103]
	v_mfma_i32_16x16x64_i8 v[92:95], v[148:151], v[202:205], v[92:95]
	v_mfma_i32_16x16x64_i8 v[84:87], v[162:165], v[202:205], v[84:87]
	v_mfma_i32_16x16x64_i8 v[76:79], v[148:151], v[210:213], v[76:79]
	v_mfma_i32_16x16x64_i8 v[68:71], v[162:165], v[210:213], v[68:71]
	v_mfma_i32_16x16x64_i8 v[120:123], v[166:169], v[182:185], v[120:123]
	v_mfma_i32_16x16x64_i8 v[112:115], v[174:177], v[182:185], v[112:115]
	v_mfma_i32_16x16x64_i8 v[104:107], v[166:169], v[190:193], v[104:107]
	v_mfma_i32_16x16x64_i8 v[96:99], v[174:177], v[190:193], v[96:99]
	v_mfma_i32_16x16x64_i8 v[88:91], v[166:169], v[198:201], v[88:91]
	v_mfma_i32_16x16x64_i8 v[80:83], v[174:177], v[198:201], v[80:83]
	v_mfma_i32_16x16x64_i8 v[72:75], v[166:169], v[206:209], v[72:75]
	v_mfma_i32_16x16x64_i8 v[64:67], v[174:177], v[206:209], v[64:67]
	v_mfma_i32_16x16x64_i8 v[120:123], v[170:173], v[186:189], v[120:123]
	v_mfma_i32_16x16x64_i8 v[112:115], v[178:181], v[186:189], v[112:115]
	v_mfma_i32_16x16x64_i8 v[104:107], v[170:173], v[194:197], v[104:107]
	v_mfma_i32_16x16x64_i8 v[96:99], v[178:181], v[194:197], v[96:99]
	v_mfma_i32_16x16x64_i8 v[88:91], v[170:173], v[202:205], v[88:91]
	v_mfma_i32_16x16x64_i8 v[80:83], v[178:181], v[202:205], v[80:83]
	v_mfma_i32_16x16x64_i8 v[72:75], v[170:173], v[210:213], v[72:75]
	v_mfma_i32_16x16x64_i8 v[64:67], v[178:181], v[210:213], v[64:67]
	s_barrier
	s_setprio 0
	s_add_i32 s53, s44, s2
	s_mov_b32 m0, s53
	ds_read_b128 v[182:185], v157 offset:16384
	ds_read_b128 v[186:189], v157 offset:17408
	ds_read_b128 v[190:193], v157 offset:18432
	ds_read_b128 v[194:197], v157 offset:19456
	ds_read_b128 v[198:201], v157 offset:20480
	global_load_lds_dwordx4 v132, s[36:37]
	s_add_i32 m0, s53, 0x2000
	s_add_u32 s54, s36, 0x80000
	s_mov_b64 s[98:99], s[36:37]
	s_addc_u32 s55, s37, 0
	s_add_i32 s53, s45, s2
	global_load_lds_dwordx4 v128, s[98:99]
	s_mov_b32 m0, s53
	s_mov_b64 s[100:101], s[38:39]
	global_load_lds_dwordx4 v132, s[54:55]
	s_add_i32 m0, s53, 0x2000
	ds_read_b128 v[202:205], v157 offset:21504
	global_load_lds_dwordx4 v128, s[54:55]
	s_mov_b64 s[100:101], s[38:39]
	s_mov_b32 m0, s17
	ds_read_b128 v[206:209], v157 offset:22528
	global_load_lds_dwordx4 v134, s[100:101]
	s_mov_b32 m0, s29
	ds_read_b128 v[210:213], v157 offset:23552
	global_load_lds_dwordx4 v130, s[100:101]
	s_waitcnt vmcnt(8) lgkmcnt(0)
	s_setprio 1
	s_barrier
	v_mfma_i32_16x16x64_i8 v[60:63], v[144:147], v[182:185], v[60:63]
	v_mfma_i32_16x16x64_i8 v[52:55], v[158:161], v[182:185], v[52:55]
	v_mfma_i32_16x16x64_i8 v[44:47], v[144:147], v[190:193], v[44:47]
	v_mfma_i32_16x16x64_i8 v[36:39], v[158:161], v[190:193], v[36:39]
	v_mfma_i32_16x16x64_i8 v[28:31], v[144:147], v[198:201], v[28:31]
	v_mfma_i32_16x16x64_i8 v[20:23], v[158:161], v[198:201], v[20:23]
	v_mfma_i32_16x16x64_i8 v[12:15], v[144:147], v[206:209], v[12:15]
	v_mfma_i32_16x16x64_i8 v[4:7], v[158:161], v[206:209], v[4:7]
	v_mfma_i32_16x16x64_i8 v[60:63], v[148:151], v[186:189], v[60:63]
	v_mfma_i32_16x16x64_i8 v[52:55], v[162:165], v[186:189], v[52:55]
	v_mfma_i32_16x16x64_i8 v[44:47], v[148:151], v[194:197], v[44:47]
	v_mfma_i32_16x16x64_i8 v[36:39], v[162:165], v[194:197], v[36:39]
	v_mfma_i32_16x16x64_i8 v[28:31], v[148:151], v[202:205], v[28:31]
	v_mfma_i32_16x16x64_i8 v[20:23], v[162:165], v[202:205], v[20:23]
	v_mfma_i32_16x16x64_i8 v[12:15], v[148:151], v[210:213], v[12:15]
	v_mfma_i32_16x16x64_i8 v[4:7], v[162:165], v[210:213], v[4:7]
	v_mfma_i32_16x16x64_i8 v[56:59], v[166:169], v[182:185], v[56:59]
	v_mfma_i32_16x16x64_i8 v[48:51], v[174:177], v[182:185], v[48:51]
	v_mfma_i32_16x16x64_i8 v[40:43], v[166:169], v[190:193], v[40:43]
	v_mfma_i32_16x16x64_i8 v[32:35], v[174:177], v[190:193], v[32:35]
	v_mfma_i32_16x16x64_i8 v[24:27], v[166:169], v[198:201], v[24:27]
	v_mfma_i32_16x16x64_i8 v[16:19], v[174:177], v[198:201], v[16:19]
	v_mfma_i32_16x16x64_i8 v[8:11], v[166:169], v[206:209], v[8:11]
	v_mfma_i32_16x16x64_i8 v[0:3], v[174:177], v[206:209], v[0:3]
	v_mfma_i32_16x16x64_i8 v[56:59], v[170:173], v[186:189], v[56:59]
	v_mfma_i32_16x16x64_i8 v[48:51], v[178:181], v[186:189], v[48:51]
	v_mfma_i32_16x16x64_i8 v[40:43], v[170:173], v[194:197], v[40:43]
	v_mfma_i32_16x16x64_i8 v[32:35], v[178:181], v[194:197], v[32:35]
	v_mfma_i32_16x16x64_i8 v[24:27], v[170:173], v[202:205], v[24:27]
	v_mfma_i32_16x16x64_i8 v[16:19], v[178:181], v[202:205], v[16:19]
	v_mfma_i32_16x16x64_i8 v[8:11], v[170:173], v[210:213], v[8:11]
	v_mfma_i32_16x16x64_i8 v[0:3], v[178:181], v[210:213], v[0:3]
	s_barrier
	s_setprio 0
	s_add_i32 s53, 0, 0x18000
	s_add_i32 s54, 0, 0x1c000
	ds_read_b128 v[144:147], v155 offset:32768
	ds_read_b128 v[148:151], v155 offset:33792
	ds_read_b128 v[158:161], v155 offset:34816
	ds_read_b128 v[162:165], v155 offset:35840
	ds_read_b128 v[166:169], v156 offset:32768
	ds_read_b128 v[170:173], v156 offset:33792
	ds_read_b128 v[174:177], v156 offset:34816
	ds_read_b128 v[178:181], v156 offset:35840
	s_add_u32 s38, s38, 0x80000
	s_addc_u32 s39, s39, 0
	s_mov_b32 m0, s33
	ds_read_b128 v[182:185], v157 offset:32768
	ds_read_b128 v[186:189], v157 offset:33792
	ds_read_b128 v[190:193], v157 offset:34816
	ds_read_b128 v[194:197], v157 offset:35840
	ds_read_b128 v[198:201], v157 offset:36864
	ds_read_b128 v[202:205], v157 offset:37888
	ds_read_b128 v[206:209], v157 offset:38912
	global_load_lds_dwordx4 v134, s[38:39]
	s_mov_b32 m0, s35
	ds_read_b128 v[210:213], v157 offset:39936
	global_load_lds_dwordx4 v130, s[38:39]
	s_waitcnt vmcnt(8) lgkmcnt(0)
	s_setprio 1
	s_barrier
	v_mfma_i32_16x16x64_i8 v[124:127], v[144:147], v[182:185], v[124:127]
	v_mfma_i32_16x16x64_i8 v[116:119], v[158:161], v[182:185], v[116:119]
	v_mfma_i32_16x16x64_i8 v[108:111], v[144:147], v[190:193], v[108:111]
	v_mfma_i32_16x16x64_i8 v[100:103], v[158:161], v[190:193], v[100:103]
	v_mfma_i32_16x16x64_i8 v[92:95], v[144:147], v[198:201], v[92:95]
	v_mfma_i32_16x16x64_i8 v[84:87], v[158:161], v[198:201], v[84:87]
	v_mfma_i32_16x16x64_i8 v[76:79], v[144:147], v[206:209], v[76:79]
	v_mfma_i32_16x16x64_i8 v[68:71], v[158:161], v[206:209], v[68:71]
	v_mfma_i32_16x16x64_i8 v[124:127], v[148:151], v[186:189], v[124:127]
	v_mfma_i32_16x16x64_i8 v[116:119], v[162:165], v[186:189], v[116:119]
	v_mfma_i32_16x16x64_i8 v[108:111], v[148:151], v[194:197], v[108:111]
	v_mfma_i32_16x16x64_i8 v[100:103], v[162:165], v[194:197], v[100:103]
	v_mfma_i32_16x16x64_i8 v[92:95], v[148:151], v[202:205], v[92:95]
	v_mfma_i32_16x16x64_i8 v[84:87], v[162:165], v[202:205], v[84:87]
	v_mfma_i32_16x16x64_i8 v[76:79], v[148:151], v[210:213], v[76:79]
	v_mfma_i32_16x16x64_i8 v[68:71], v[162:165], v[210:213], v[68:71]
	v_mfma_i32_16x16x64_i8 v[120:123], v[166:169], v[182:185], v[120:123]
	v_mfma_i32_16x16x64_i8 v[112:115], v[174:177], v[182:185], v[112:115]
	v_mfma_i32_16x16x64_i8 v[104:107], v[166:169], v[190:193], v[104:107]
	v_mfma_i32_16x16x64_i8 v[96:99], v[174:177], v[190:193], v[96:99]
	v_mfma_i32_16x16x64_i8 v[88:91], v[166:169], v[198:201], v[88:91]
	v_mfma_i32_16x16x64_i8 v[80:83], v[174:177], v[198:201], v[80:83]
	v_mfma_i32_16x16x64_i8 v[72:75], v[166:169], v[206:209], v[72:75]
	v_mfma_i32_16x16x64_i8 v[64:67], v[174:177], v[206:209], v[64:67]
	v_mfma_i32_16x16x64_i8 v[120:123], v[170:173], v[186:189], v[120:123]
	v_mfma_i32_16x16x64_i8 v[112:115], v[178:181], v[186:189], v[112:115]
	v_mfma_i32_16x16x64_i8 v[104:107], v[170:173], v[194:197], v[104:107]
	v_mfma_i32_16x16x64_i8 v[96:99], v[178:181], v[194:197], v[96:99]
	v_mfma_i32_16x16x64_i8 v[88:91], v[170:173], v[202:205], v[88:91]
	v_mfma_i32_16x16x64_i8 v[80:83], v[178:181], v[202:205], v[80:83]
	v_mfma_i32_16x16x64_i8 v[72:75], v[170:173], v[210:213], v[72:75]
	v_mfma_i32_16x16x64_i8 v[64:67], v[178:181], v[210:213], v[64:67]
	s_barrier
	s_setprio 0
	s_add_i32 s38, s53, s2
	s_add_i32 m0, s38, -128
	ds_read_b128 v[182:185], v157 offset:49152
	ds_read_b128 v[186:189], v157 offset:50176
	ds_read_b128 v[190:193], v157 offset:51200
	ds_read_b128 v[194:197], v157 offset:52224
	global_load_lds_dwordx4 v132, s[36:37] offset:128
	s_add_i32 m0, s38, 8064
	s_add_u32 s36, s36, 0x80080
	s_addc_u32 s37, s37, 0
	s_add_i32 s38, s54, s2
	global_load_lds_dwordx4 v128, s[98:99] offset:128
	s_mov_b32 m0, s38
	ds_read_b128 v[198:201], v157 offset:53248
	global_load_lds_dwordx4 v132, s[36:37]
	s_add_i32 m0, s38, 0x2000
	ds_read_b128 v[202:205], v157 offset:54272
	global_load_lds_dwordx4 v128, s[36:37]
	s_add_i32 m0, s42, -128
	ds_read_b128 v[206:209], v157 offset:55296
	global_load_lds_dwordx4 v134, s[100:101] offset:128
	s_add_i32 m0, s43, -128
	ds_read_b128 v[210:213], v157 offset:56320
	global_load_lds_dwordx4 v130, s[100:101] offset:128
	s_waitcnt vmcnt(8) lgkmcnt(0)
	s_setprio 1
	s_barrier
	v_mfma_i32_16x16x64_i8 v[60:63], v[144:147], v[182:185], v[60:63]
	v_mfma_i32_16x16x64_i8 v[52:55], v[158:161], v[182:185], v[52:55]
	v_mfma_i32_16x16x64_i8 v[44:47], v[144:147], v[190:193], v[44:47]
	v_mfma_i32_16x16x64_i8 v[36:39], v[158:161], v[190:193], v[36:39]
	v_mfma_i32_16x16x64_i8 v[28:31], v[144:147], v[198:201], v[28:31]
	v_mfma_i32_16x16x64_i8 v[20:23], v[158:161], v[198:201], v[20:23]
	v_mfma_i32_16x16x64_i8 v[12:15], v[144:147], v[206:209], v[12:15]
	v_mfma_i32_16x16x64_i8 v[4:7], v[158:161], v[206:209], v[4:7]
	v_mfma_i32_16x16x64_i8 v[60:63], v[148:151], v[186:189], v[60:63]
	v_mfma_i32_16x16x64_i8 v[52:55], v[162:165], v[186:189], v[52:55]
	v_mfma_i32_16x16x64_i8 v[44:47], v[148:151], v[194:197], v[44:47]
	v_mfma_i32_16x16x64_i8 v[36:39], v[162:165], v[194:197], v[36:39]
	v_mfma_i32_16x16x64_i8 v[28:31], v[148:151], v[202:205], v[28:31]
	v_mfma_i32_16x16x64_i8 v[20:23], v[162:165], v[202:205], v[20:23]
	v_mfma_i32_16x16x64_i8 v[12:15], v[148:151], v[210:213], v[12:15]
	v_mfma_i32_16x16x64_i8 v[4:7], v[162:165], v[210:213], v[4:7]
	v_mfma_i32_16x16x64_i8 v[56:59], v[166:169], v[182:185], v[56:59]
	v_mfma_i32_16x16x64_i8 v[48:51], v[174:177], v[182:185], v[48:51]
	v_mfma_i32_16x16x64_i8 v[40:43], v[166:169], v[190:193], v[40:43]
	v_mfma_i32_16x16x64_i8 v[32:35], v[174:177], v[190:193], v[32:35]
	v_mfma_i32_16x16x64_i8 v[24:27], v[166:169], v[198:201], v[24:27]
	v_mfma_i32_16x16x64_i8 v[16:19], v[174:177], v[198:201], v[16:19]
	v_mfma_i32_16x16x64_i8 v[8:11], v[166:169], v[206:209], v[8:11]
	v_mfma_i32_16x16x64_i8 v[0:3], v[174:177], v[206:209], v[0:3]
	v_mfma_i32_16x16x64_i8 v[56:59], v[170:173], v[186:189], v[56:59]
	v_mfma_i32_16x16x64_i8 v[48:51], v[178:181], v[186:189], v[48:51]
	v_mfma_i32_16x16x64_i8 v[40:43], v[170:173], v[194:197], v[40:43]
	v_mfma_i32_16x16x64_i8 v[32:35], v[178:181], v[194:197], v[32:35]
	v_mfma_i32_16x16x64_i8 v[24:27], v[170:173], v[202:205], v[24:27]
	v_mfma_i32_16x16x64_i8 v[16:19], v[178:181], v[202:205], v[16:19]
	v_mfma_i32_16x16x64_i8 v[8:11], v[170:173], v[210:213], v[8:11]
	v_mfma_i32_16x16x64_i8 v[0:3], v[178:181], v[210:213], v[0:3]
	s_barrier
	s_setprio 0
	s_add_i32 s52, s52, 2
	s_add_u32 s30, s30, 0x100
	s_addc_u32 s31, s31, 0
	s_add_u32 s50, s50, 0x100
	s_addc_u32 s51, s51, 0
	s_cmp_gt_u32 s52, 29
	s_cbranch_scc0 .LBB0_773
	s_and_b64 vcc, exec, s[14:15]
	s_cbranch_vccz .LBB0_776
	s_barrier

.LBB0_858:
	ds_read_b128 v[152:155], v149
	ds_read_b128 v[156:159], v149 offset:1024
	ds_read_b128 v[160:163], v149 offset:2048
	ds_read_b128 v[164:167], v149 offset:3072
	ds_read_b128 v[168:171], v150
	ds_read_b128 v[172:175], v150 offset:1024
	ds_read_b128 v[176:179], v150 offset:2048
	ds_read_b128 v[180:183], v150 offset:3072
	s_add_u32 s26, s24, 0x100
	s_addc_u32 s27, s25, 0
	s_cmpk_eq_i32 s54, 0xa8
	s_cselect_b32 s31, s5, s27
	s_cselect_b32 s30, s4, s26
	s_cselect_b32 s29, s23, s53
	s_cselect_b32 s28, s22, s52
	s_add_i32 m0, s33, 0xc000
	ds_read_b128 v[184:187], v151
	ds_read_b128 v[188:191], v151 offset:1024
	ds_read_b128 v[192:195], v151 offset:2048
	ds_read_b128 v[196:199], v151 offset:3072
	ds_read_b128 v[200:203], v151 offset:4096
	ds_read_b128 v[204:207], v151 offset:5120
	ds_read_b128 v[208:211], v151 offset:6144
	global_load_lds_dwordx4 v136, s[24:25]
	s_add_i32 m0, s33, 0xe000
	ds_read_b128 v[212:215], v151 offset:7168
	global_load_lds_dwordx4 v138, s[24:25]
	s_waitcnt vmcnt(8) lgkmcnt(0)
	s_setprio 1
	s_barrier
	v_mfma_f32_16x16x32_bf16 v[124:127], v[152:155], v[184:187], v[124:127]
	v_mfma_f32_16x16x32_bf16 v[120:123], v[160:163], v[184:187], v[120:123]
	v_mfma_f32_16x16x32_bf16 v[116:119], v[152:155], v[192:195], v[116:119]
	v_mfma_f32_16x16x32_bf16 v[108:111], v[160:163], v[192:195], v[108:111]
	v_mfma_f32_16x16x32_bf16 v[100:103], v[152:155], v[200:203], v[100:103]
	v_mfma_f32_16x16x32_bf16 v[92:95], v[160:163], v[200:203], v[92:95]
	v_mfma_f32_16x16x32_bf16 v[84:87], v[152:155], v[208:211], v[84:87]
	v_mfma_f32_16x16x32_bf16 v[76:79], v[160:163], v[208:211], v[76:79]
	v_mfma_f32_16x16x32_bf16 v[124:127], v[156:159], v[188:191], v[124:127]
	v_mfma_f32_16x16x32_bf16 v[120:123], v[164:167], v[188:191], v[120:123]
	v_mfma_f32_16x16x32_bf16 v[116:119], v[156:159], v[196:199], v[116:119]
	v_mfma_f32_16x16x32_bf16 v[108:111], v[164:167], v[196:199], v[108:111]
	v_mfma_f32_16x16x32_bf16 v[100:103], v[156:159], v[204:207], v[100:103]
	v_mfma_f32_16x16x32_bf16 v[92:95], v[164:167], v[204:207], v[92:95]
	v_mfma_f32_16x16x32_bf16 v[84:87], v[156:159], v[212:215], v[84:87]
	v_mfma_f32_16x16x32_bf16 v[76:79], v[164:167], v[212:215], v[76:79]
	v_mfma_f32_16x16x32_bf16 v[112:115], v[168:171], v[184:187], v[112:115]
	v_mfma_f32_16x16x32_bf16 v[104:107], v[176:179], v[184:187], v[104:107]
	v_mfma_f32_16x16x32_bf16 v[96:99], v[168:171], v[192:195], v[96:99]
	v_mfma_f32_16x16x32_bf16 v[88:91], v[176:179], v[192:195], v[88:91]
	v_mfma_f32_16x16x32_bf16 v[80:83], v[168:171], v[200:203], v[80:83]
	v_mfma_f32_16x16x32_bf16 v[72:75], v[176:179], v[200:203], v[72:75]
	v_mfma_f32_16x16x32_bf16 v[68:71], v[168:171], v[208:211], v[68:71]
	v_mfma_f32_16x16x32_bf16 v[64:67], v[176:179], v[208:211], v[64:67]
	v_mfma_f32_16x16x32_bf16 v[112:115], v[172:175], v[188:191], v[112:115]
	v_mfma_f32_16x16x32_bf16 v[104:107], v[180:183], v[188:191], v[104:107]
	v_mfma_f32_16x16x32_bf16 v[96:99], v[172:175], v[196:199], v[96:99]
	v_mfma_f32_16x16x32_bf16 v[88:91], v[180:183], v[196:199], v[88:91]
	v_mfma_f32_16x16x32_bf16 v[80:83], v[172:175], v[204:207], v[80:83]
	v_mfma_f32_16x16x32_bf16 v[72:75], v[180:183], v[204:207], v[72:75]
	v_mfma_f32_16x16x32_bf16 v[68:71], v[172:175], v[212:215], v[68:71]
	v_mfma_f32_16x16x32_bf16 v[64:67], v[180:183], v[212:215], v[64:67]
	s_barrier
	s_setprio 0
	s_add_i32 s24, s42, s2
	s_mov_b32 m0, s24
	ds_read_b128 v[184:187], v151 offset:16384
	ds_read_b128 v[188:191], v151 offset:17408
	ds_read_b128 v[192:195], v151 offset:18432
	ds_read_b128 v[196:199], v151 offset:19456
	global_load_lds_dwordx4 v132, s[28:29]
	s_add_i32 m0, s24, 0x2000
	s_add_u32 s24, s28, 0x2b0000
	s_mov_b64 s[98:99], s[28:29]
	s_addc_u32 s25, s29, 0
	s_add_i32 s55, s43, s2
	global_load_lds_dwordx4 v128, s[98:99]
	s_mov_b32 m0, s55
	ds_read_b128 v[200:203], v151 offset:20480
	global_load_lds_dwordx4 v132, s[24:25]
	s_add_i32 m0, s55, 0x2000
	ds_read_b128 v[204:207], v151 offset:21504
	global_load_lds_dwordx4 v128, s[24:25]
	s_mov_b32 m0, s33
	ds_read_b128 v[208:211], v151 offset:22528
	global_load_lds_dwordx4 v134, s[30:31]
	s_mov_b32 m0, s35
	ds_read_b128 v[212:215], v151 offset:23552
	global_load_lds_dwordx4 v130, s[30:31]
	s_waitcnt vmcnt(8) lgkmcnt(0)
	s_setprio 1
	s_barrier
	v_mfma_f32_16x16x32_bf16 v[60:63], v[152:155], v[184:187], v[60:63]
	v_mfma_f32_16x16x32_bf16 v[56:59], v[160:163], v[184:187], v[56:59]
	v_mfma_f32_16x16x32_bf16 v[52:55], v[152:155], v[192:195], v[52:55]
	v_mfma_f32_16x16x32_bf16 v[44:47], v[160:163], v[192:195], v[44:47]
	v_mfma_f32_16x16x32_bf16 v[36:39], v[152:155], v[200:203], v[36:39]
	v_mfma_f32_16x16x32_bf16 v[28:31], v[160:163], v[200:203], v[28:31]
	v_mfma_f32_16x16x32_bf16 v[20:23], v[152:155], v[208:211], v[20:23]
	v_mfma_f32_16x16x32_bf16 v[12:15], v[160:163], v[208:211], v[12:15]
	v_mfma_f32_16x16x32_bf16 v[60:63], v[156:159], v[188:191], v[60:63]
	v_mfma_f32_16x16x32_bf16 v[56:59], v[164:167], v[188:191], v[56:59]
	v_mfma_f32_16x16x32_bf16 v[52:55], v[156:159], v[196:199], v[52:55]
	v_mfma_f32_16x16x32_bf16 v[44:47], v[164:167], v[196:199], v[44:47]
	v_mfma_f32_16x16x32_bf16 v[36:39], v[156:159], v[204:207], v[36:39]
	v_mfma_f32_16x16x32_bf16 v[28:31], v[164:167], v[204:207], v[28:31]
	v_mfma_f32_16x16x32_bf16 v[20:23], v[156:159], v[212:215], v[20:23]
	v_mfma_f32_16x16x32_bf16 v[12:15], v[164:167], v[212:215], v[12:15]
	v_mfma_f32_16x16x32_bf16 v[48:51], v[168:171], v[184:187], v[48:51]
	v_mfma_f32_16x16x32_bf16 v[40:43], v[176:179], v[184:187], v[40:43]
	v_mfma_f32_16x16x32_bf16 v[32:35], v[168:171], v[192:195], v[32:35]
	v_mfma_f32_16x16x32_bf16 v[24:27], v[176:179], v[192:195], v[24:27]
	v_mfma_f32_16x16x32_bf16 v[16:19], v[168:171], v[200:203], v[16:19]
	v_mfma_f32_16x16x32_bf16 v[8:11], v[176:179], v[200:203], v[8:11]
	v_mfma_f32_16x16x32_bf16 v[4:7], v[168:171], v[208:211], v[4:7]
	v_mfma_f32_16x16x32_bf16 v[0:3], v[176:179], v[208:211], v[0:3]
	v_mfma_f32_16x16x32_bf16 v[48:51], v[172:175], v[188:191], v[48:51]
	v_mfma_f32_16x16x32_bf16 v[40:43], v[180:183], v[188:191], v[40:43]
	v_mfma_f32_16x16x32_bf16 v[32:35], v[172:175], v[196:199], v[32:35]
	v_mfma_f32_16x16x32_bf16 v[24:27], v[180:183], v[196:199], v[24:27]
	v_mfma_f32_16x16x32_bf16 v[16:19], v[172:175], v[204:207], v[16:19]
	v_mfma_f32_16x16x32_bf16 v[8:11], v[180:183], v[204:207], v[8:11]
	v_mfma_f32_16x16x32_bf16 v[4:7], v[172:175], v[212:215], v[4:7]
	v_mfma_f32_16x16x32_bf16 v[0:3], v[180:183], v[212:215], v[0:3]
	s_barrier
	s_setprio 0
	s_add_i32 s55, 0, 0x18000
	s_add_i32 s58, 0, 0x1c000
	ds_read_b128 v[152:155], v149 offset:32768
	ds_read_b128 v[156:159], v149 offset:33792
	ds_read_b128 v[160:163], v149 offset:34816
	ds_read_b128 v[164:167], v149 offset:35840
	ds_read_b128 v[168:171], v150 offset:32768
	ds_read_b128 v[172:175], v150 offset:33792
	ds_read_b128 v[176:179], v150 offset:34816
	ds_read_b128 v[180:183], v150 offset:35840
	s_add_u32 s24, s30, 0x2b0000
	s_addc_u32 s25, s31, 0
	s_mov_b32 m0, s36
	ds_read_b128 v[184:187], v151 offset:32768
	ds_read_b128 v[188:191], v151 offset:33792
	ds_read_b128 v[192:195], v151 offset:34816
	ds_read_b128 v[196:199], v151 offset:35840
	ds_read_b128 v[200:203], v151 offset:36864
	ds_read_b128 v[204:207], v151 offset:37888
	ds_read_b128 v[208:211], v151 offset:38912
	global_load_lds_dwordx4 v134, s[24:25]
	s_mov_b32 m0, s37
	ds_read_b128 v[212:215], v151 offset:39936
	global_load_lds_dwordx4 v130, s[24:25]
	s_waitcnt vmcnt(8) lgkmcnt(0)
	s_setprio 1
	s_barrier
	v_mfma_f32_16x16x32_bf16 v[124:127], v[152:155], v[184:187], v[124:127]
	v_mfma_f32_16x16x32_bf16 v[120:123], v[160:163], v[184:187], v[120:123]
	v_mfma_f32_16x16x32_bf16 v[116:119], v[152:155], v[192:195], v[116:119]
	v_mfma_f32_16x16x32_bf16 v[108:111], v[160:163], v[192:195], v[108:111]
	v_mfma_f32_16x16x32_bf16 v[100:103], v[152:155], v[200:203], v[100:103]
	v_mfma_f32_16x16x32_bf16 v[92:95], v[160:163], v[200:203], v[92:95]
	v_mfma_f32_16x16x32_bf16 v[84:87], v[152:155], v[208:211], v[84:87]
	v_mfma_f32_16x16x32_bf16 v[76:79], v[160:163], v[208:211], v[76:79]
	v_mfma_f32_16x16x32_bf16 v[124:127], v[156:159], v[188:191], v[124:127]
	v_mfma_f32_16x16x32_bf16 v[120:123], v[164:167], v[188:191], v[120:123]
	v_mfma_f32_16x16x32_bf16 v[116:119], v[156:159], v[196:199], v[116:119]
	v_mfma_f32_16x16x32_bf16 v[108:111], v[164:167], v[196:199], v[108:111]
	v_mfma_f32_16x16x32_bf16 v[100:103], v[156:159], v[204:207], v[100:103]
	v_mfma_f32_16x16x32_bf16 v[92:95], v[164:167], v[204:207], v[92:95]
	v_mfma_f32_16x16x32_bf16 v[84:87], v[156:159], v[212:215], v[84:87]
	v_mfma_f32_16x16x32_bf16 v[76:79], v[164:167], v[212:215], v[76:79]
	v_mfma_f32_16x16x32_bf16 v[112:115], v[168:171], v[184:187], v[112:115]
	v_mfma_f32_16x16x32_bf16 v[104:107], v[176:179], v[184:187], v[104:107]
	v_mfma_f32_16x16x32_bf16 v[96:99], v[168:171], v[192:195], v[96:99]
	v_mfma_f32_16x16x32_bf16 v[88:91], v[176:179], v[192:195], v[88:91]
	v_mfma_f32_16x16x32_bf16 v[80:83], v[168:171], v[200:203], v[80:83]
	v_mfma_f32_16x16x32_bf16 v[72:75], v[176:179], v[200:203], v[72:75]
	v_mfma_f32_16x16x32_bf16 v[68:71], v[168:171], v[208:211], v[68:71]
	v_mfma_f32_16x16x32_bf16 v[64:67], v[176:179], v[208:211], v[64:67]
	v_mfma_f32_16x16x32_bf16 v[112:115], v[172:175], v[188:191], v[112:115]
	v_mfma_f32_16x16x32_bf16 v[104:107], v[180:183], v[188:191], v[104:107]
	v_mfma_f32_16x16x32_bf16 v[96:99], v[172:175], v[196:199], v[96:99]
	v_mfma_f32_16x16x32_bf16 v[88:91], v[180:183], v[196:199], v[88:91]
	v_mfma_f32_16x16x32_bf16 v[80:83], v[172:175], v[204:207], v[80:83]
	v_mfma_f32_16x16x32_bf16 v[72:75], v[180:183], v[204:207], v[72:75]
	v_mfma_f32_16x16x32_bf16 v[68:71], v[172:175], v[212:215], v[68:71]
	v_mfma_f32_16x16x32_bf16 v[64:67], v[180:183], v[212:215], v[64:67]
	s_barrier
	s_setprio 0
	s_add_i32 s24, s55, s2
	s_add_i32 m0, s24, -128
	ds_read_b128 v[184:187], v151 offset:49152
	ds_read_b128 v[188:191], v151 offset:50176
	ds_read_b128 v[192:195], v151 offset:51200
	ds_read_b128 v[196:199], v151 offset:52224
	global_load_lds_dwordx4 v132, s[28:29] offset:128
	s_add_i32 m0, s24, 8064
	s_add_u32 s24, s28, 0x2b0080
	s_addc_u32 s25, s29, 0
	s_add_i32 s28, s58, s2
	global_load_lds_dwordx4 v128, s[98:99] offset:128
	s_mov_b32 m0, s28
	ds_read_b128 v[200:203], v151 offset:53248
	global_load_lds_dwordx4 v132, s[24:25]
	s_add_i32 m0, s28, 0x2000
	ds_read_b128 v[204:207], v151 offset:54272
	global_load_lds_dwordx4 v128, s[24:25]
	s_add_i32 m0, s40, -128
	ds_read_b128 v[208:211], v151 offset:55296
	global_load_lds_dwordx4 v134, s[30:31] offset:128
	s_add_i32 m0, s41, -128
	ds_read_b128 v[212:215], v151 offset:56320
	global_load_lds_dwordx4 v130, s[30:31] offset:128
	s_waitcnt vmcnt(8) lgkmcnt(0)
	s_setprio 1
	s_barrier
	v_mfma_f32_16x16x32_bf16 v[60:63], v[152:155], v[184:187], v[60:63]
	v_mfma_f32_16x16x32_bf16 v[56:59], v[160:163], v[184:187], v[56:59]
	v_mfma_f32_16x16x32_bf16 v[52:55], v[152:155], v[192:195], v[52:55]
	v_mfma_f32_16x16x32_bf16 v[44:47], v[160:163], v[192:195], v[44:47]
	v_mfma_f32_16x16x32_bf16 v[36:39], v[152:155], v[200:203], v[36:39]
	v_mfma_f32_16x16x32_bf16 v[28:31], v[160:163], v[200:203], v[28:31]
	v_mfma_f32_16x16x32_bf16 v[20:23], v[152:155], v[208:211], v[20:23]
	v_mfma_f32_16x16x32_bf16 v[12:15], v[160:163], v[208:211], v[12:15]
	v_mfma_f32_16x16x32_bf16 v[60:63], v[156:159], v[188:191], v[60:63]
	v_mfma_f32_16x16x32_bf16 v[56:59], v[164:167], v[188:191], v[56:59]
	v_mfma_f32_16x16x32_bf16 v[52:55], v[156:159], v[196:199], v[52:55]
	v_mfma_f32_16x16x32_bf16 v[44:47], v[164:167], v[196:199], v[44:47]
	v_mfma_f32_16x16x32_bf16 v[36:39], v[156:159], v[204:207], v[36:39]
	v_mfma_f32_16x16x32_bf16 v[28:31], v[164:167], v[204:207], v[28:31]
	v_mfma_f32_16x16x32_bf16 v[20:23], v[156:159], v[212:215], v[20:23]
	v_mfma_f32_16x16x32_bf16 v[12:15], v[164:167], v[212:215], v[12:15]
	v_mfma_f32_16x16x32_bf16 v[48:51], v[168:171], v[184:187], v[48:51]
	v_mfma_f32_16x16x32_bf16 v[40:43], v[176:179], v[184:187], v[40:43]
	v_mfma_f32_16x16x32_bf16 v[32:35], v[168:171], v[192:195], v[32:35]
	v_mfma_f32_16x16x32_bf16 v[24:27], v[176:179], v[192:195], v[24:27]
	v_mfma_f32_16x16x32_bf16 v[16:19], v[168:171], v[200:203], v[16:19]
	v_mfma_f32_16x16x32_bf16 v[8:11], v[176:179], v[200:203], v[8:11]
	v_mfma_f32_16x16x32_bf16 v[4:7], v[168:171], v[208:211], v[4:7]
	v_mfma_f32_16x16x32_bf16 v[0:3], v[176:179], v[208:211], v[0:3]
	v_mfma_f32_16x16x32_bf16 v[48:51], v[172:175], v[188:191], v[48:51]
	v_mfma_f32_16x16x32_bf16 v[40:43], v[180:183], v[188:191], v[40:43]
	v_mfma_f32_16x16x32_bf16 v[32:35], v[172:175], v[196:199], v[32:35]
	v_mfma_f32_16x16x32_bf16 v[24:27], v[180:183], v[196:199], v[24:27]
	v_mfma_f32_16x16x32_bf16 v[16:19], v[172:175], v[204:207], v[16:19]
	v_mfma_f32_16x16x32_bf16 v[8:11], v[180:183], v[204:207], v[8:11]
	v_mfma_f32_16x16x32_bf16 v[4:7], v[172:175], v[212:215], v[4:7]
	v_mfma_f32_16x16x32_bf16 v[0:3], v[180:183], v[212:215], v[0:3]
	s_barrier
	s_setprio 0
	s_add_i32 s54, s54, 2
	s_add_u32 s52, s52, 0x100
	s_addc_u32 s53, s53, 0
	s_cmpk_gt_u32 s54, 0xa9
	s_mov_b64 s[24:25], s[26:27]
	s_cbranch_scc0 .LBB0_858
	s_and_b64 vcc, exec, s[10:11]
	s_cbranch_vccz .LBB0_861
	s_barrier
